# conv phase: the layer's taps and biases staged in LDS once per phase, read per item with ds_read_b128 instead of 16 global loads
# baseline (speedup 1.0000x reference)
; __device__ __forceinline__ int ltid(int wv) { unsigned z = 0u; asm volatile("" : "+v"(z)); return wv * 64 + (int)__builtin_amdgcn_mbcnt_hi(~0u, __builtin_amdgcn_mbcnt_lo(~0u, z)); }
; __device__ __forceinline__ int lgrid() { int g = gridDim.x; asm volatile("" : "+s"(g)); return g; }
; __device__ __forceinline__ int lbid() { int b = blockIdx.x; asm volatile("" : "+s"(b)); return b; }
; __device__ __forceinline__ void conv_pass(const bf16_t* __restrict__ U, const float* __restrict__ cw, const float* __restrict__ cb, bf16_t* __restrict__ GA, int tg, int wv) {
;     const int gt = lbid() * 512 + ltid(wv), NGT = lgrid() * 512;
;     constexpr int NCH = DFF / 8, RUN = 8; const int NITEM = (tg / RUN) * NCH;
;     for (int it = gt; it < NITEM; it += NGT) {
;         const int ch = it % NCH, run = it / NCH, c0 = ch * 8, t0 = run * RUN;
;         const u32x4 zero = {0u, 0u, 0u, 0u};
;         u32x4 ra[RUN + 2], rb[RUN + 2];
; #pragma unroll
;         for (int i = 0; i < RUN + 2; ++i) {
;             const int t = t0 - 1 + i;
;             const bool ok = !((i == 0 && (t0 & (SEQ - 1)) == 0) || (i == RUN + 1 && ((t0 + RUN) & (SEQ - 1)) == 0));
;             const bf16_t* p = U + (size_t)(ok ? t : t0) * DFF2 + c0;
;             const u32x4 a = *(const u32x4*)p, b = *(const u32x4*)(p + DFF);
;             ra[i] = ok ? a : zero; rb[i] = ok ? b : zero;
;         }
.LBB0_184:
	s_andn2_b64 vcc, exec, s[2:3]
	s_cbranch_vccnz .LBB0_269
	s_cmp_lt_i32 s63, 9
	s_mov_b64 s[2:3], -1
	s_cbranch_scc1 .LBB0_233
	s_cmp_gt_i32 s63, 9
	s_cbranch_scc0 .LBB0_191
	v_readlane_b32 s0, v255, 0
	v_mov_b32_e32 v0, v1
	s_lshl_b32 s0, s0, 9
	v_readlane_b32 s1, v255, 1
	v_readlane_b32 s2, v255, 16
	v_mbcnt_lo_u32_b32 v0, -1, v0
	s_add_i32 s0, s0, s1
	v_readlane_b32 s3, v255, 17
	v_mbcnt_hi_u32_b32 v0, -1, v0
	s_and_b64 s[2:3], s[2:3], exec
	s_mov_b32 s1, 0xb0000
	v_add_u32_e32 v0, s0, v0
	s_cselect_b32 s22, 0x160000, s1
	s_mov_b32 s0, s33
	v_cmp_gt_i32_e32 vcc, s22, v0
	s_and_saveexec_b64 s[8:9], vcc
	s_cbranch_execz .LBB0_190
	v_readlane_b32 s2, v255, 12
	v_readlane_b32 s3, v255, 13
	s_load_dwordx4 s[64:67], s[2:3], 0x90
	s_add_u32 s12, s18, 0xa200000
	s_mul_i32 s1, s14, 0x10800
	s_addc_u32 s13, s19, 0
	s_mul_i32 s2, s14, 0x5800
	s_waitcnt lgkmcnt(0)
	s_add_u32 s64, s64, s1
	s_addc_u32 s65, s65, 0
	s_add_u32 s66, s66, s2
	s_addc_u32 s67, s67, 0
	s_add_u32 s68, s18, 0x20200000
	s_addc_u32 s69, s19, 0
	s_lshl_b32 s28, s0, 9
	s_add_u32 s70, s66, 0x2c00
	s_addc_u32 s71, s67, 0
	s_add_u32 s72, s64, 0x2c00
	s_addc_u32 s73, s65, 0
	s_add_u32 s74, s64, 0x5800
	s_addc_u32 s75, s65, 0
	s_add_u32 s76, s64, 0x8400
	s_addc_u32 s77, s65, 0
	s_add_u32 s78, s64, 0xb000
	s_addc_u32 s79, s65, 0
	s_add_u32 s80, s64, 0xdc00
	s_addc_u32 s81, s65, 0
	v_lshlrev_b32_e32 v154, 3, v0
	s_lshl_b32 s46, s0, 12
	s_mov_b64 s[82:83], 0
	v_mbcnt_lo_u32_b32 v200, -1, 0
	v_mbcnt_hi_u32_b32 v200, -1, v200
	v_lshlrev_b32_e32 v200, 4, v200
	v_readlane_b32 s1, v255, 1
	s_nop 3
	s_lshr_b32 s1, s1, 6
.Lconv_fill:
	s_lshl_b32 s2, s1, 10
	s_sub_u32 s3, s2, 0x10800
	s_cmp_lt_u32 s1, 66
	s_cselect_b32 s20, s64, s66
	s_cselect_b32 s21, s65, s67
	s_cselect_b32 s3, s2, s3
	s_add_u32 s20, s20, s3
	s_addc_u32 s21, s21, 0
	s_mov_b32 m0, s2
	s_nop 0
	global_load_lds_dwordx4 v200, s[20:21]
	s_add_i32 s1, s1, 8
	s_cmp_lt_u32 s1, 88
	s_cbranch_scc1 .Lconv_fill
	s_waitcnt vmcnt(0)
	s_barrier
.LBB0_189:
	s_mov_b32 s0, 0x2e8ba2e9
	v_mul_hi_i32 v2, v0, s0
	v_lshrrev_b32_e32 v3, 31, v2
	v_ashrrev_i32_e32 v2, 6, v2
	v_add_u32_e32 v2, v2, v3
	v_mul_i32_i24_e32 v3, 0x160, v2
	v_lshlrev_b32_e32 v3, 3, v3
	v_sub_u32_e32 v10, v154, v3
	v_lshlrev_b32_e32 v170, 3, v2
	v_and_b32_e32 v2, 0x3ff, v2
	v_ashrrev_i32_e32 v11, 31, v10
	v_lshlrev_b64 v[130:131], 1, v[10:11]
	v_cmp_ne_u32_e64 s[2:3], 0, v2
	v_add_u32_e32 v14, 8, v170
	v_lshl_add_u64 v[12:13], s[12:13], 0, v[130:131]
	v_subbrev_co_u32_e64 v2, s[4:5], 0, v170, s[2:3]
	v_and_b32_e32 v3, 0x1ff8, v14
	v_mad_i64_i32 v[6:7], s[0:1], v2, s95, v[12:13]
	v_cmp_eq_u32_e32 vcc, 0, v3
	global_load_dwordx4 v[2:5], v[6:7], off
	v_add_co_u32_e64 v6, s[4:5], s93, v6
	v_or_b32_e32 v169, 1, v170
	s_nop 0
	v_addc_co_u32_e64 v7, s[4:5], 0, v7, s[4:5]
	global_load_dwordx4 v[6:9], v[6:7], off offset:1536
	v_or_b32_e32 v168, 2, v170
	v_or_b32_e32 v167, 3, v170
	v_or_b32_e32 v166, 4, v170
	v_or_b32_e32 v165, 5, v170
	v_or_b32_e32 v163, 6, v170
	v_or_b32_e32 v155, 7, v170
	v_lshl_add_u64 v[130:131], s[68:69], 0, v[130:131]
	v_add_u32_e32 v0, s28, v0
	v_add_u32_e32 v154, s46, v154
	s_waitcnt vmcnt(0)
	v_cndmask_b32_e64 v150, 0, v3, s[2:3]
	v_cndmask_b32_e64 v133, 0, v2, s[2:3]
	v_mad_i64_i32 v[2:3], s[0:1], v170, s95, v[12:13]
	v_cndmask_b32_e64 v152, 0, v5, s[2:3]
	v_cndmask_b32_e64 v138, 0, v4, s[2:3]
	global_load_dwordx4 v[118:121], v[2:3], off
	s_waitcnt vmcnt(1)
	v_cndmask_b32_e64 v171, 0, v9, s[2:3]
	v_cndmask_b32_e64 v153, 0, v8, s[2:3]
	v_cndmask_b32_e64 v139, 0, v7, s[2:3]
	v_cndmask_b32_e64 v140, 0, v6, s[2:3]
	v_add_co_u32_e64 v2, s[2:3], s93, v2
	v_lshlrev_b32_e32 v132, 16, v133
	s_nop 0
	v_addc_co_u32_e64 v3, s[2:3], 0, v3, s[2:3]
	global_load_dwordx4 v[114:117], v[2:3], off offset:1536
	v_mad_i64_i32 v[2:3], s[0:1], v169, s95, v[12:13]
	global_load_dwordx4 v[126:129], v[2:3], off
	v_add_co_u32_e64 v2, s[2:3], s93, v2
	v_and_b32_e32 v133, 0xffff0000, v133
	s_nop 0
	v_addc_co_u32_e64 v3, s[2:3], 0, v3, s[2:3]
	global_load_dwordx4 v[122:125], v[2:3], off offset:1536
	v_mad_i64_i32 v[2:3], s[0:1], v168, s95, v[12:13]
	global_load_dwordx4 v[110:113], v[2:3], off
	v_add_co_u32_e64 v2, s[2:3], s93, v2
	s_waitcnt vmcnt(4)
	v_lshlrev_b32_e32 v146, 16, v118
	v_addc_co_u32_e64 v3, s[2:3], 0, v3, s[2:3]
	global_load_dwordx4 v[106:109], v[2:3], off offset:1536
	v_mad_i64_i32 v[2:3], s[0:1], v167, s95, v[12:13]
	global_load_dwordx4 v[102:105], v[2:3], off
	v_add_co_u32_e64 v2, s[2:3], s93, v2
	v_and_b32_e32 v147, 0xffff0000, v118
	s_nop 0
	v_addc_co_u32_e64 v3, s[2:3], 0, v3, s[2:3]
	global_load_dwordx4 v[98:101], v[2:3], off offset:1536
	v_mad_i64_i32 v[2:3], s[0:1], v166, s95, v[12:13]
	global_load_dwordx4 v[94:97], v[2:3], off
	v_add_co_u32_e64 v2, s[2:3], s93, v2
	s_waitcnt vmcnt(7)
	v_and_b32_e32 v141, 0xffff0000, v114
	v_addc_co_u32_e64 v3, s[2:3], 0, v3, s[2:3]
	global_load_dwordx4 v[90:93], v[2:3], off offset:1536
	v_mad_i64_i32 v[2:3], s[0:1], v165, s95, v[12:13]
	global_load_dwordx4 v[86:89], v[2:3], off
	v_add_co_u32_e64 v2, s[2:3], s93, v2
	v_and_b32_e32 v151, 0xffff0000, v120
	s_nop 0
	v_addc_co_u32_e64 v3, s[2:3], 0, v3, s[2:3]
	global_load_dwordx4 v[82:85], v[2:3], off offset:1536
	v_mad_i64_i32 v[2:3], s[0:1], v163, s95, v[12:13]
	global_load_dwordx4 v[78:81], v[2:3], off
	v_add_co_u32_e64 v2, s[2:3], s93, v2
	s_nop 1
	v_addc_co_u32_e64 v3, s[2:3], 0, v3, s[2:3]
	global_load_dwordx4 v[74:77], v[2:3], off offset:1536
	v_mad_i64_i32 v[2:3], s[0:1], v155, s95, v[12:13]
	global_load_dwordx4 v[70:73], v[2:3], off
	v_add_co_u32_e64 v2, s[2:3], s93, v2
	s_nop 1
	v_addc_co_u32_e64 v3, s[2:3], 0, v3, s[2:3]
	global_load_dwordx4 v[66:69], v[2:3], off offset:1536
	v_cndmask_b32_e32 v2, v14, v170, vcc
	v_mad_i64_i32 v[6:7], s[0:1], v2, s95, v[12:13]
	global_load_dwordx4 v[2:5], v[6:7], off
	v_add_co_u32_e64 v6, s[2:3], s93, v6
	v_lshlrev_b64 v[14:15], 2, v[10:11]
	v_mov_b32_e32 v200, v14
	v_add_u32_e32 v201, 0x10800, v14
	s_nop 0
	v_addc_co_u32_e64 v7, s[2:3], 0, v7, s[2:3]
	global_load_dwordx4 v[6:9], v[6:7], off offset:1536
	v_lshl_add_u64 v[10:11], s[76:77], 0, v[14:15]
	v_lshl_add_u64 v[16:17], s[80:81], 0, v[14:15]
	v_lshl_add_u64 v[54:55], s[70:71], 0, v[14:15]
	s_waitcnt vmcnt(1)
; __device__ __forceinline__ float gelu_tanh(float x) { const float u = 0.7978845608028654f * (x + 0.044715f * x * x * x); return x * sigmoidf_(2.0f * u); }
; __device__ __forceinline__ float bfe(const u32x4& w, int e) { return (e & 1) ? __builtin_bit_cast(float, w[e >> 1] & 0xffff0000u) : __builtin_bit_cast(float, w[e >> 1] << 16); }
; __device__ __forceinline__ void conv_pass(const bf16_t* __restrict__ U, const float* __restrict__ cw, const float* __restrict__ cb, bf16_t* __restrict__ GA, int tg, int wv) {
;     ...
;         f32x4 wa[3][2], wb[3][2], ba[2], bb[2];
; #pragma unroll
;         for (int k = 0; k < 3; ++k) { wa[k][0] = *(const f32x4*)(cw + k * DFF2 + c0); wa[k][1] = *(const f32x4*)(cw + k * DFF2 + c0 + 4);
;                                       wb[k][0] = *(const f32x4*)(cw + k * DFF2 + DFF + c0); wb[k][1] = *(const f32x4*)(cw + k * DFF2 + DFF + c0 + 4); }
;         ba[0] = *(const f32x4*)(cb + c0); ba[1] = *(const f32x4*)(cb + c0 + 4); bb[0] = *(const f32x4*)(cb + DFF + c0); bb[1] = *(const f32x4*)(cb + DFF + c0 + 4);
; #pragma unroll
;         for (int i = 0; i < RUN; ++i) {
;             float o[8];
; #pragma unroll
;             for (int e = 0; e < 8; ++e) {
;                 const float ua = bfe(ra[i], e) * wa[0][e >> 2][e & 3] + bfe(ra[i + 1], e) * wa[1][e >> 2][e & 3] + bfe(ra[i + 2], e) * wa[2][e >> 2][e & 3] + ba[e >> 2][e & 3];
;                 const float ub = bfe(rb[i], e) * wb[0][e >> 2][e & 3] + bfe(rb[i + 1], e) * wb[1][e >> 2][e & 3] + bfe(rb[i + 2], e) * wb[2][e >> 2][e & 3] + bb[e >> 2][e & 3];
;                 o[e] = gelu_tanh(ua) * ub;
	v_cndmask_b32_e64 v161, v3, 0, vcc
	v_cndmask_b32_e64 v164, v2, 0, vcc
	v_lshl_add_u64 v[2:3], s[64:65], 0, v[14:15]
	v_cndmask_b32_e64 v157, v5, 0, vcc
	v_cndmask_b32_e64 v159, v4, 0, vcc
	ds_read_b128 v[18:21], v200 offset:16
	ds_read_b128 v[38:41], v200 offset:0
	s_waitcnt vmcnt(0)
	v_cndmask_b32_e64 v160, v7, 0, vcc
	v_cndmask_b32_e64 v162, v6, 0, vcc
	v_lshl_add_u64 v[6:7], s[72:73], 0, v[14:15]
	ds_read_b128 v[2:5], v200 offset:11280
	ds_read_b128 v[34:37], v200 offset:11264
	v_lshl_add_u64 v[6:7], s[74:75], 0, v[14:15]
	ds_read_b128 v[30:33], v200 offset:22544
	ds_read_b128 v[50:53], v200 offset:22528
	v_cndmask_b32_e64 v156, v9, 0, vcc
	v_cndmask_b32_e64 v158, v8, 0, vcc
	ds_read_b128 v[6:9], v200 offset:33808
	ds_read_b128 v[42:45], v200 offset:33792
	v_lshl_add_u64 v[10:11], s[78:79], 0, v[14:15]
	ds_read_b128 v[22:25], v200 offset:45072
	ds_read_b128 v[58:61], v200 offset:45056
	s_nop 0
	ds_read_b128 v[10:13], v200 offset:56336
	ds_read_b128 v[46:49], v200 offset:56320
	v_lshl_add_u64 v[16:17], s[66:67], 0, v[14:15]
	ds_read_b128 v[26:29], v201 offset:16
	ds_read_b128 v[62:65], v201 offset:0
	s_nop 0
	ds_read_b128 v[14:17], v201 offset:11280
	s_nop 0
	ds_read_b128 v[54:57], v201 offset:11264
	v_cmp_le_i32_e32 vcc, s22, v0
	s_or_b64 s[82:83], vcc, s[82:83]
	s_waitcnt lgkmcnt(0)
	s_waitcnt vmcnt(0)
	v_pk_mul_f32 v[134:135], v[50:51], v[146:147]
	s_nop 0
	v_pk_fma_f32 v[132:133], v[38:39], v[132:133], v[134:135]
	v_lshlrev_b32_e32 v134, 16, v126
	v_and_b32_e32 v135, 0xffff0000, v126
	v_lshlrev_b32_e32 v126, 16, v139
	s_waitcnt vmcnt(0)
	v_pk_fma_f32 v[132:133], v[58:59], v[134:135], v[132:133]
	s_waitcnt vmcnt(0)
	v_pk_add_f32 v[136:137], v[132:133], v[62:63]
	s_nop 0
	v_mul_f32_e32 v118, 0x3d372713, v136
	v_lshlrev_b32_e32 v132, 16, v140
	v_and_b32_e32 v133, 0xffff0000, v140
	v_lshlrev_b32_e32 v140, 16, v114
	v_mul_f32_e32 v114, 0x3d372713, v137
	v_mul_f32_e32 v118, v136, v118
	v_mul_f32_e32 v114, v137, v114
	v_fma_f32 v118, v136, v118, v136
	v_fma_f32 v114, v137, v114, v137
	v_mul_f32_e32 v118, 0x3f4c422a, v118
	v_mul_f32_e32 v114, 0x3f4c422a, v114
	v_add_f32_e32 v118, v118, v118
	v_add_f32_e32 v114, v114, v114
	v_mul_f32_e32 v118, 0xbfb8aa3b, v118
	v_mul_f32_e32 v114, 0xbfb8aa3b, v114
	v_exp_f32_e32 v118, v118
	v_exp_f32_e32 v114, v114
	v_pk_mul_f32 v[144:145], v[42:43], v[140:141]
	v_add_f32_e32 v118, 1.0, v118
	v_add_f32_e32 v114, 1.0, v114
	v_rcp_f32_e32 v142, v118
	v_rcp_f32_e32 v143, v114
	v_pk_fma_f32 v[144:145], v[34:35], v[132:133], v[144:145]
	v_lshlrev_b32_e32 v132, 16, v122
	v_and_b32_e32 v133, 0xffff0000, v122
	v_pk_fma_f32 v[144:145], v[46:47], v[132:133], v[144:145]
	v_pk_mul_f32 v[136:137], v[136:137], v[142:143]
	s_waitcnt vmcnt(0)
	v_pk_add_f32 v[144:145], v[144:145], v[54:55]
	v_lshlrev_b32_e32 v142, 16, v115
	v_pk_mul_f32 v[148:149], v[144:145], v[136:137]
	v_lshlrev_b32_e32 v144, 16, v119
	v_and_b32_e32 v145, 0xffff0000, v119
	v_lshlrev_b32_e32 v136, 16, v150
	v_and_b32_e32 v137, 0xffff0000, v150
	v_pk_mul_f32 v[118:119], v[52:53], v[144:145]
	v_and_b32_e32 v143, 0xffff0000, v115
	v_pk_fma_f32 v[118:119], v[40:41], v[136:137], v[118:119]
	v_lshlrev_b32_e32 v136, 16, v127
	v_and_b32_e32 v137, 0xffff0000, v127
	v_pk_fma_f32 v[118:119], v[60:61], v[136:137], v[118:119]
	v_and_b32_e32 v127, 0xffff0000, v139
	v_pk_add_f32 v[118:119], v[118:119], v[64:65]
	v_lshlrev_b32_e32 v150, 16, v120
	v_mul_f32_e32 v114, 0x3d372713, v118
	v_mul_f32_e32 v114, v118, v114
	v_fma_f32 v114, v118, v114, v118
	v_mul_f32_e32 v114, 0x3f4c422a, v114
	v_add_f32_e32 v114, v114, v114
	v_mul_f32_e32 v114, 0xbfb8aa3b, v114
	v_exp_f32_e32 v114, v114
	v_and_b32_e32 v139, 0xffff0000, v128
	v_add_f32_e32 v114, 1.0, v114
	v_rcp_f32_e32 v122, v114
	v_pk_mul_f32 v[114:115], v[44:45], v[142:143]
	s_nop 0
	v_pk_fma_f32 v[126:127], v[36:37], v[126:127], v[114:115]
	v_lshlrev_b32_e32 v114, 16, v123
	v_and_b32_e32 v115, 0xffff0000, v123
	v_mul_f32_e32 v123, 0x3d372713, v119
	v_mul_f32_e32 v123, v119, v123
	v_fma_f32 v123, v119, v123, v119
	v_mul_f32_e32 v123, 0x3f4c422a, v123
	v_add_f32_e32 v123, v123, v123
	v_mul_f32_e32 v123, 0xbfb8aa3b, v123
	v_exp_f32_e32 v123, v123
	v_pk_fma_f32 v[126:127], v[48:49], v[114:115], v[126:127]
	v_add_f32_e32 v123, 1.0, v123
	v_rcp_f32_e32 v123, v123
	v_pk_add_f32 v[126:127], v[126:127], v[56:57]
	v_pk_mul_f32 v[118:119], v[118:119], v[122:123]
	s_nop 0
	v_pk_mul_f32 v[126:127], v[126:127], v[118:119]
	v_lshlrev_b32_e32 v118, 16, v138
	v_and_b32_e32 v119, 0xffff0000, v138
	v_pk_mul_f32 v[122:123], v[30:31], v[150:151]
	v_lshlrev_b32_e32 v138, 16, v128
	v_pk_fma_f32 v[118:119], v[18:19], v[118:119], v[122:123]
	v_lshlrev_b32_e32 v122, 16, v116
	v_pk_fma_f32 v[118:119], v[22:23], v[138:139], v[118:119]
	v_and_b32_e32 v123, 0xffff0000, v116
	v_pk_add_f32 v[172:173], v[118:119], v[26:27]
	v_and_b32_e32 v119, 0xffff0000, v153
	v_mul_f32_e32 v118, 0x3d372713, v172
	v_mul_f32_e32 v116, 0x3d372713, v173
	v_mul_f32_e32 v118, v172, v118
	v_mul_f32_e32 v116, v173, v116
	v_fma_f32 v118, v172, v118, v172
	v_fma_f32 v116, v173, v116, v173
	v_mul_f32_e32 v118, 0x3f4c422a, v118
	v_mul_f32_e32 v116, 0x3f4c422a, v116
	v_add_f32_e32 v118, v118, v118
	v_add_f32_e32 v116, v116, v116
	v_mul_f32_e32 v118, 0xbfb8aa3b, v118
	v_mul_f32_e32 v116, 0xbfb8aa3b, v116
	v_exp_f32_e32 v118, v118
	v_exp_f32_e32 v116, v116
	v_lshlrev_b32_e32 v128, 16, v129
	v_and_b32_e32 v129, 0xffff0000, v129
	v_add_f32_e32 v118, 1.0, v118
	v_add_f32_e32 v116, 1.0, v116
	v_rcp_f32_e32 v174, v118
	v_rcp_f32_e32 v175, v116
	v_lshlrev_b32_e32 v118, 16, v153
	v_and_b32_e32 v153, 0xffff0000, v121
	v_pk_mul_f32 v[176:177], v[6:7], v[122:123]
	v_pk_mul_f32 v[172:173], v[172:173], v[174:175]
; __device__ __forceinline__ unsigned cvtpk(float lo, float hi) { f32x2 v = {lo, hi}; bf16x2_t b = __builtin_convertvector(v, bf16x2_t); return __builtin_bit_cast(unsigned, b); }
; __device__ __forceinline__ float gelu_tanh(float x) { const float u = 0.7978845608028654f * (x + 0.044715f * x * x * x); return x * sigmoidf_(2.0f * u); }
; __device__ __forceinline__ void st16_wt(void* p, u32x4 v) { asm volatile("global_store_dwordx4 %0, %1, off sc1\n\ts_nop 2" :: "v"(p), "v"(v) : "memory"); }
; __device__ __forceinline__ float bfe(const u32x4& w, int e) { return (e & 1) ? __builtin_bit_cast(float, w[e >> 1] & 0xffff0000u) : __builtin_bit_cast(float, w[e >> 1] << 16); }
; __device__ __forceinline__ void conv_pass(const bf16_t* __restrict__ U, const float* __restrict__ cw, const float* __restrict__ cb, bf16_t* __restrict__ GA, int tg, int wv) {
;     ...
; #pragma unroll
;         for (int i = 0; i < RUN; ++i) {
;             float o[8];
; #pragma unroll
;             for (int e = 0; e < 8; ++e) {
;                 const float ua = bfe(ra[i], e) * wa[0][e >> 2][e & 3] + bfe(ra[i + 1], e) * wa[1][e >> 2][e & 3] + bfe(ra[i + 2], e) * wa[2][e >> 2][e & 3] + ba[e >> 2][e & 3];
;                 const float ub = bfe(rb[i], e) * wb[0][e >> 2][e & 3] + bfe(rb[i + 1], e) * wb[1][e >> 2][e & 3] + bfe(rb[i + 2], e) * wb[2][e >> 2][e & 3] + bb[e >> 2][e & 3];
;                 o[e] = gelu_tanh(ua) * ub;
;             }
;             u32x4 w; w.x = cvtpk(o[0], o[1]); w.y = cvtpk(o[2], o[3]); w.z = cvtpk(o[4], o[5]); w.w = cvtpk(o[6], o[7]);
;             st16_wt(GA + (size_t)(t0 + i) * DFF + c0, w);
	v_lshlrev_b32_e32 v174, 16, v152
	v_and_b32_e32 v175, 0xffff0000, v152
	v_lshlrev_b32_e32 v152, 16, v121
	v_pk_mul_f32 v[120:121], v[32:33], v[152:153]
	v_pk_fma_f32 v[176:177], v[2:3], v[118:119], v[176:177]
	v_pk_fma_f32 v[120:121], v[20:21], v[174:175], v[120:121]
	v_lshlrev_b32_e32 v118, 16, v124
	v_pk_fma_f32 v[120:121], v[24:25], v[128:129], v[120:121]
	v_and_b32_e32 v119, 0xffff0000, v124
	v_pk_add_f32 v[174:175], v[120:121], v[28:29]
	v_pk_fma_f32 v[176:177], v[10:11], v[118:119], v[176:177]
	v_mul_f32_e32 v116, 0x3d372713, v174
	v_mul_f32_e32 v116, v174, v116
	v_fma_f32 v116, v174, v116, v174
	v_mul_f32_e32 v116, 0x3f4c422a, v116
	v_add_f32_e32 v116, v116, v116
	v_mul_f32_e32 v116, 0xbfb8aa3b, v116
	v_exp_f32_e32 v116, v116
	v_pk_add_f32 v[176:177], v[176:177], v[14:15]
	v_lshlrev_b32_e32 v120, 16, v117
	v_and_b32_e32 v121, 0xffff0000, v117
	v_add_f32_e32 v116, 1.0, v116
	v_pk_mul_f32 v[172:173], v[176:177], v[172:173]
	v_rcp_f32_e32 v124, v116
	v_lshlrev_b32_e32 v176, 16, v171
	v_and_b32_e32 v177, 0xffff0000, v171
	v_pk_mul_f32 v[116:117], v[8:9], v[120:121]
	s_nop 0
	v_pk_fma_f32 v[176:177], v[4:5], v[176:177], v[116:117]
	v_lshlrev_b32_e32 v116, 16, v125
	v_and_b32_e32 v117, 0xffff0000, v125
	v_mul_f32_e32 v125, 0x3d372713, v175
	v_mul_f32_e32 v125, v175, v125
	v_fma_f32 v125, v175, v125, v175
	v_mul_f32_e32 v125, 0x3f4c422a, v125
	v_add_f32_e32 v125, v125, v125
	v_mul_f32_e32 v125, 0xbfb8aa3b, v125
	v_exp_f32_e32 v125, v125
	v_pk_fma_f32 v[176:177], v[12:13], v[116:117], v[176:177]
	v_add_f32_e32 v125, 1.0, v125
	v_rcp_f32_e32 v125, v125
	v_pk_add_f32 v[176:177], v[176:177], v[16:17]
	v_pk_mul_f32 v[124:125], v[174:175], v[124:125]
	s_nop 0
	v_pk_mul_f32 v[174:175], v[176:177], v[124:125]
	v_cvt_pk_bf16_f32 v124, v148, v149
	v_cvt_pk_bf16_f32 v125, v126, v127
	v_cvt_pk_bf16_f32 v126, v172, v173
	v_cvt_pk_bf16_f32 v127, v174, v175
	v_mad_i64_i32 v[148:149], s[0:1], v170, s91, v[130:131]
	global_store_dwordx4 v[148:149], v[124:127], off sc1 nt
	s_nop 2
	v_pk_mul_f32 v[124:125], v[50:51], v[134:135]
	v_lshlrev_b32_e32 v148, 16, v110
	v_pk_fma_f32 v[124:125], v[38:39], v[146:147], v[124:125]
	v_and_b32_e32 v149, 0xffff0000, v110
	v_pk_fma_f32 v[124:125], v[58:59], v[148:149], v[124:125]
	v_pk_mul_f32 v[126:127], v[42:43], v[132:133]
	v_pk_add_f32 v[124:125], v[124:125], v[62:63]
	v_pk_fma_f32 v[140:141], v[34:35], v[140:141], v[126:127]
	v_mul_f32_e32 v110, 0x3d372713, v124
	v_lshlrev_b32_e32 v126, 16, v106
	v_and_b32_e32 v127, 0xffff0000, v106
	v_mul_f32_e32 v106, 0x3d372713, v125
	v_mul_f32_e32 v110, v124, v110
	v_mul_f32_e32 v106, v125, v106
	v_fma_f32 v110, v124, v110, v124
	v_fma_f32 v106, v125, v106, v125
	v_mul_f32_e32 v110, 0x3f4c422a, v110
	v_mul_f32_e32 v106, 0x3f4c422a, v106
	v_add_f32_e32 v110, v110, v110
	v_add_f32_e32 v106, v106, v106
	v_mul_f32_e32 v110, 0xbfb8aa3b, v110
	v_mul_f32_e32 v106, 0xbfb8aa3b, v106
	v_exp_f32_e32 v110, v110
	v_exp_f32_e32 v106, v106
	v_pk_fma_f32 v[140:141], v[46:47], v[126:127], v[140:141]
	v_add_f32_e32 v110, 1.0, v110
	v_add_f32_e32 v106, 1.0, v106
	v_rcp_f32_e32 v146, v110
	v_rcp_f32_e32 v147, v106
	v_pk_add_f32 v[140:141], v[140:141], v[54:55]
	v_pk_mul_f32 v[124:125], v[124:125], v[146:147]
	s_nop 0
	v_pk_mul_f32 v[146:147], v[140:141], v[124:125]
	v_pk_mul_f32 v[124:125], v[52:53], v[136:137]
	s_nop 0
	v_pk_fma_f32 v[124:125], v[40:41], v[144:145], v[124:125]
	v_lshlrev_b32_e32 v144, 16, v111
	v_and_b32_e32 v145, 0xffff0000, v111
	v_pk_fma_f32 v[110:111], v[60:61], v[144:145], v[124:125]
	v_pk_mul_f32 v[124:125], v[44:45], v[114:115]
	v_pk_add_f32 v[110:111], v[110:111], v[64:65]
	v_pk_fma_f32 v[140:141], v[36:37], v[142:143], v[124:125]
	v_mul_f32_e32 v106, 0x3d372713, v110
	v_lshlrev_b32_e32 v124, 16, v107
	v_and_b32_e32 v125, 0xffff0000, v107
	v_mul_f32_e32 v107, 0x3d372713, v111
	v_mul_f32_e32 v106, v110, v106
	v_mul_f32_e32 v107, v111, v107
	v_fma_f32 v106, v110, v106, v110
	v_fma_f32 v107, v111, v107, v111
	v_mul_f32_e32 v106, 0x3f4c422a, v106
	v_mul_f32_e32 v107, 0x3f4c422a, v107
	v_add_f32_e32 v106, v106, v106
	v_add_f32_e32 v107, v107, v107
	v_mul_f32_e32 v106, 0xbfb8aa3b, v106
	v_mul_f32_e32 v107, 0xbfb8aa3b, v107
	v_exp_f32_e32 v106, v106
	v_exp_f32_e32 v107, v107
	v_pk_fma_f32 v[140:141], v[48:49], v[124:125], v[140:141]
	v_lshlrev_b32_e32 v142, 16, v112
	v_add_f32_e32 v106, 1.0, v106
	v_add_f32_e32 v107, 1.0, v107
	v_rcp_f32_e32 v106, v106
	v_rcp_f32_e32 v107, v107
	v_pk_add_f32 v[140:141], v[140:141], v[56:57]
	v_and_b32_e32 v143, 0xffff0000, v112
	v_pk_mul_f32 v[106:107], v[110:111], v[106:107]
	s_nop 0
	v_pk_mul_f32 v[110:111], v[140:141], v[106:107]
	v_pk_mul_f32 v[106:107], v[30:31], v[138:139]
	s_nop 0
	v_pk_fma_f32 v[106:107], v[18:19], v[150:151], v[106:107]
	v_pk_mul_f32 v[150:151], v[6:7], v[118:119]
	v_pk_fma_f32 v[106:107], v[22:23], v[142:143], v[106:107]
	v_pk_fma_f32 v[150:151], v[2:3], v[122:123], v[150:151]
	v_pk_add_f32 v[106:107], v[106:107], v[26:27]
	v_lshlrev_b32_e32 v122, 16, v108
	v_mul_f32_e32 v112, 0x3d372713, v106
	v_and_b32_e32 v123, 0xffff0000, v108
	v_mul_f32_e32 v108, 0x3d372713, v107
	v_mul_f32_e32 v112, v106, v112
	v_mul_f32_e32 v108, v107, v108
	v_fma_f32 v112, v106, v112, v106
	v_fma_f32 v108, v107, v108, v107
	v_mul_f32_e32 v112, 0x3f4c422a, v112
	v_mul_f32_e32 v108, 0x3f4c422a, v108
	v_add_f32_e32 v112, v112, v112
	v_add_f32_e32 v108, v108, v108
	v_mul_f32_e32 v112, 0xbfb8aa3b, v112
	v_mul_f32_e32 v108, 0xbfb8aa3b, v108
	v_exp_f32_e32 v112, v112
	v_exp_f32_e32 v108, v108
	v_pk_fma_f32 v[150:151], v[10:11], v[122:123], v[150:151]
	v_add_f32_e32 v112, 1.0, v112
	v_add_f32_e32 v108, 1.0, v108
	v_rcp_f32_e32 v140, v112
; __device__ __forceinline__ unsigned cvtpk(float lo, float hi) { f32x2 v = {lo, hi}; bf16x2_t b = __builtin_convertvector(v, bf16x2_t); return __builtin_bit_cast(unsigned, b); }
; __device__ __forceinline__ float gelu_tanh(float x) { const float u = 0.7978845608028654f * (x + 0.044715f * x * x * x); return x * sigmoidf_(2.0f * u); }
; __device__ __forceinline__ void st16_wt(void* p, u32x4 v) { asm volatile("global_store_dwordx4 %0, %1, off sc1\n\ts_nop 2" :: "v"(p), "v"(v) : "memory"); }
; __device__ __forceinline__ float bfe(const u32x4& w, int e) { return (e & 1) ? __builtin_bit_cast(float, w[e >> 1] & 0xffff0000u) : __builtin_bit_cast(float, w[e >> 1] << 16); }
; __device__ __forceinline__ void conv_pass(const bf16_t* __restrict__ U, const float* __restrict__ cw, const float* __restrict__ cb, bf16_t* __restrict__ GA, int tg, int wv) {
;     ...
; #pragma unroll
;         for (int i = 0; i < RUN; ++i) {
;             float o[8];
; #pragma unroll
;             for (int e = 0; e < 8; ++e) {
;                 const float ua = bfe(ra[i], e) * wa[0][e >> 2][e & 3] + bfe(ra[i + 1], e) * wa[1][e >> 2][e & 3] + bfe(ra[i + 2], e) * wa[2][e >> 2][e & 3] + ba[e >> 2][e & 3];
;                 const float ub = bfe(rb[i], e) * wb[0][e >> 2][e & 3] + bfe(rb[i + 1], e) * wb[1][e >> 2][e & 3] + bfe(rb[i + 2], e) * wb[2][e >> 2][e & 3] + bb[e >> 2][e & 3];
;                 o[e] = gelu_tanh(ua) * ub;
;             }
;             u32x4 w; w.x = cvtpk(o[0], o[1]); w.y = cvtpk(o[2], o[3]); w.z = cvtpk(o[4], o[5]); w.w = cvtpk(o[6], o[7]);
;             st16_wt(GA + (size_t)(t0 + i) * DFF + c0, w);
	v_rcp_f32_e32 v141, v108
	v_pk_add_f32 v[150:151], v[150:151], v[14:15]
	v_pk_mul_f32 v[106:107], v[106:107], v[140:141]
	s_nop 0
	v_pk_mul_f32 v[150:151], v[150:151], v[106:107]
	v_pk_mul_f32 v[106:107], v[32:33], v[128:129]
	v_lshlrev_b32_e32 v140, 16, v113
	v_pk_fma_f32 v[106:107], v[20:21], v[152:153], v[106:107]
	v_and_b32_e32 v141, 0xffff0000, v113
	v_pk_fma_f32 v[106:107], v[24:25], v[140:141], v[106:107]
	v_pk_mul_f32 v[112:113], v[8:9], v[116:117]
	v_pk_add_f32 v[106:107], v[106:107], v[28:29]
	v_pk_fma_f32 v[112:113], v[4:5], v[120:121], v[112:113]
	v_mul_f32_e32 v108, 0x3d372713, v106
	v_lshlrev_b32_e32 v120, 16, v109
	v_and_b32_e32 v121, 0xffff0000, v109
	v_mul_f32_e32 v109, 0x3d372713, v107
	v_mul_f32_e32 v108, v106, v108
	v_mul_f32_e32 v109, v107, v109
	v_fma_f32 v108, v106, v108, v106
	v_fma_f32 v109, v107, v109, v107
	v_mul_f32_e32 v108, 0x3f4c422a, v108
	v_mul_f32_e32 v109, 0x3f4c422a, v109
	v_add_f32_e32 v108, v108, v108
	v_add_f32_e32 v109, v109, v109
	v_mul_f32_e32 v108, 0xbfb8aa3b, v108
	v_mul_f32_e32 v109, 0xbfb8aa3b, v109
	v_exp_f32_e32 v108, v108
	v_exp_f32_e32 v109, v109
	v_pk_fma_f32 v[112:113], v[12:13], v[120:121], v[112:113]
	v_add_f32_e32 v108, 1.0, v108
	v_add_f32_e32 v109, 1.0, v109
	v_rcp_f32_e32 v108, v108
	v_rcp_f32_e32 v109, v109
	v_pk_add_f32 v[112:113], v[112:113], v[16:17]
	v_pk_mul_f32 v[106:107], v[106:107], v[108:109]
	s_nop 0
	v_pk_mul_f32 v[112:113], v[112:113], v[106:107]
	v_cvt_pk_bf16_f32 v106, v146, v147
	v_cvt_pk_bf16_f32 v107, v110, v111
	v_cvt_pk_bf16_f32 v108, v150, v151
	v_cvt_pk_bf16_f32 v109, v112, v113
	v_mad_i64_i32 v[110:111], s[0:1], v169, s91, v[130:131]
	global_store_dwordx4 v[110:111], v[106:109], off sc1 nt
	s_nop 2
	v_pk_mul_f32 v[106:107], v[50:51], v[148:149]
	v_lshlrev_b32_e32 v146, 16, v102
	v_pk_fma_f32 v[106:107], v[38:39], v[134:135], v[106:107]
	v_and_b32_e32 v147, 0xffff0000, v102
	v_pk_fma_f32 v[106:107], v[58:59], v[146:147], v[106:107]
	v_lshlrev_b32_e32 v112, 16, v98
	v_pk_add_f32 v[106:107], v[106:107], v[62:63]
	v_and_b32_e32 v113, 0xffff0000, v98
	v_mul_f32_e32 v102, 0x3d372713, v106
	v_mul_f32_e32 v98, 0x3d372713, v107
	v_mul_f32_e32 v102, v106, v102
	v_mul_f32_e32 v98, v107, v98
	v_fma_f32 v102, v106, v102, v106
	v_fma_f32 v98, v107, v98, v107
	v_mul_f32_e32 v102, 0x3f4c422a, v102
	v_mul_f32_e32 v98, 0x3f4c422a, v98
	v_add_f32_e32 v102, v102, v102
	v_add_f32_e32 v98, v98, v98
	v_mul_f32_e32 v102, 0xbfb8aa3b, v102
	v_mul_f32_e32 v98, 0xbfb8aa3b, v98
	v_exp_f32_e32 v102, v102
	v_exp_f32_e32 v98, v98
	v_lshlrev_b32_e32 v134, 16, v103
	v_and_b32_e32 v135, 0xffff0000, v103
	v_add_f32_e32 v102, 1.0, v102
	v_add_f32_e32 v98, 1.0, v98
	v_rcp_f32_e32 v108, v102
	v_rcp_f32_e32 v109, v98
	v_pk_mul_f32 v[110:111], v[42:43], v[126:127]
	v_pk_mul_f32 v[106:107], v[106:107], v[108:109]
	v_pk_mul_f32 v[108:109], v[52:53], v[144:145]
	v_pk_fma_f32 v[110:111], v[34:35], v[132:133], v[110:111]
	v_pk_fma_f32 v[108:109], v[40:41], v[136:137], v[108:109]
	v_pk_fma_f32 v[110:111], v[46:47], v[112:113], v[110:111]
	v_pk_fma_f32 v[102:103], v[60:61], v[134:135], v[108:109]
	v_pk_add_f32 v[110:111], v[110:111], v[54:55]
	v_pk_add_f32 v[102:103], v[102:103], v[64:65]
	v_pk_mul_f32 v[106:107], v[110:111], v[106:107]
	v_mul_f32_e32 v98, 0x3d372713, v102
	v_mul_f32_e32 v109, 0x3d372713, v103
	v_mul_f32_e32 v98, v102, v98
	v_mul_f32_e32 v109, v103, v109
	v_fma_f32 v98, v102, v98, v102
	v_fma_f32 v109, v103, v109, v103
	v_mul_f32_e32 v98, 0x3f4c422a, v98
	v_mul_f32_e32 v109, 0x3f4c422a, v109
	v_add_f32_e32 v98, v98, v98
	v_add_f32_e32 v109, v109, v109
	v_mul_f32_e32 v98, 0xbfb8aa3b, v98
	v_mul_f32_e32 v109, 0xbfb8aa3b, v109
	v_exp_f32_e32 v98, v98
	v_exp_f32_e32 v109, v109
	v_pk_mul_f32 v[110:111], v[44:45], v[124:125]
	v_lshlrev_b32_e32 v132, 16, v104
	v_add_f32_e32 v98, 1.0, v98
	v_add_f32_e32 v109, 1.0, v109
	v_rcp_f32_e32 v108, v98
	v_rcp_f32_e32 v109, v109
	v_pk_fma_f32 v[110:111], v[36:37], v[114:115], v[110:111]
	v_lshlrev_b32_e32 v98, 16, v99
	v_and_b32_e32 v99, 0xffff0000, v99
	v_pk_mul_f32 v[102:103], v[102:103], v[108:109]
	v_pk_mul_f32 v[108:109], v[30:31], v[142:143]
	v_pk_fma_f32 v[110:111], v[48:49], v[98:99], v[110:111]
	v_pk_fma_f32 v[108:109], v[18:19], v[138:139], v[108:109]
	v_and_b32_e32 v133, 0xffff0000, v104
	v_pk_add_f32 v[110:111], v[110:111], v[56:57]
	v_pk_fma_f32 v[108:109], v[22:23], v[132:133], v[108:109]
	v_pk_mul_f32 v[102:103], v[110:111], v[102:103]
	v_pk_add_f32 v[108:109], v[108:109], v[26:27]
	v_pk_mul_f32 v[110:111], v[6:7], v[122:123]
	v_mul_f32_e32 v104, 0x3d372713, v108
	v_pk_fma_f32 v[118:119], v[2:3], v[118:119], v[110:111]
	v_lshlrev_b32_e32 v110, 16, v100
	v_and_b32_e32 v111, 0xffff0000, v100
	v_mul_f32_e32 v100, 0x3d372713, v109
	v_mul_f32_e32 v104, v108, v104
	v_mul_f32_e32 v100, v109, v100
	v_fma_f32 v104, v108, v104, v108
	v_fma_f32 v100, v109, v100, v109
	v_mul_f32_e32 v104, 0x3f4c422a, v104
	v_mul_f32_e32 v100, 0x3f4c422a, v100
	v_add_f32_e32 v104, v104, v104
	v_add_f32_e32 v100, v100, v100
	v_mul_f32_e32 v104, 0xbfb8aa3b, v104
	v_mul_f32_e32 v100, 0xbfb8aa3b, v100
	v_exp_f32_e32 v104, v104
	v_exp_f32_e32 v100, v100
	v_pk_fma_f32 v[118:119], v[10:11], v[110:111], v[118:119]
	v_lshlrev_b32_e32 v136, 16, v94
	v_add_f32_e32 v104, 1.0, v104
	v_add_f32_e32 v100, 1.0, v100
	v_rcp_f32_e32 v114, v104
	v_rcp_f32_e32 v115, v100
	v_pk_add_f32 v[118:119], v[118:119], v[14:15]
	v_and_b32_e32 v137, 0xffff0000, v94
	v_pk_mul_f32 v[108:109], v[108:109], v[114:115]
	s_nop 0
	v_pk_mul_f32 v[114:115], v[118:119], v[108:109]
	v_pk_mul_f32 v[108:109], v[32:33], v[140:141]
	v_lshlrev_b32_e32 v118, 16, v96
	v_pk_fma_f32 v[108:109], v[20:21], v[128:129], v[108:109]
; __device__ __forceinline__ unsigned cvtpk(float lo, float hi) { f32x2 v = {lo, hi}; bf16x2_t b = __builtin_convertvector(v, bf16x2_t); return __builtin_bit_cast(unsigned, b); }
; __device__ __forceinline__ float gelu_tanh(float x) { const float u = 0.7978845608028654f * (x + 0.044715f * x * x * x); return x * sigmoidf_(2.0f * u); }
; __device__ __forceinline__ void st16_wt(void* p, u32x4 v) { asm volatile("global_store_dwordx4 %0, %1, off sc1\n\ts_nop 2" :: "v"(p), "v"(v) : "memory"); }
; __device__ __forceinline__ float bfe(const u32x4& w, int e) { return (e & 1) ? __builtin_bit_cast(float, w[e >> 1] & 0xffff0000u) : __builtin_bit_cast(float, w[e >> 1] << 16); }
; __device__ __forceinline__ void conv_pass(const bf16_t* __restrict__ U, const float* __restrict__ cw, const float* __restrict__ cb, bf16_t* __restrict__ GA, int tg, int wv) {
;     ...
; #pragma unroll
;         for (int i = 0; i < RUN; ++i) {
;             float o[8];
; #pragma unroll
;             for (int e = 0; e < 8; ++e) {
;                 const float ua = bfe(ra[i], e) * wa[0][e >> 2][e & 3] + bfe(ra[i + 1], e) * wa[1][e >> 2][e & 3] + bfe(ra[i + 2], e) * wa[2][e >> 2][e & 3] + ba[e >> 2][e & 3];
;                 const float ub = bfe(rb[i], e) * wb[0][e >> 2][e & 3] + bfe(rb[i + 1], e) * wb[1][e >> 2][e & 3] + bfe(rb[i + 2], e) * wb[2][e >> 2][e & 3] + bb[e >> 2][e & 3];
;                 o[e] = gelu_tanh(ua) * ub;
;             }
;             u32x4 w; w.x = cvtpk(o[0], o[1]); w.y = cvtpk(o[2], o[3]); w.z = cvtpk(o[4], o[5]); w.w = cvtpk(o[6], o[7]);
;             st16_wt(GA + (size_t)(t0 + i) * DFF + c0, w);
	v_lshlrev_b32_e32 v128, 16, v105
	v_and_b32_e32 v129, 0xffff0000, v105
	v_pk_fma_f32 v[104:105], v[24:25], v[128:129], v[108:109]
	v_pk_mul_f32 v[108:109], v[8:9], v[120:121]
	v_pk_add_f32 v[104:105], v[104:105], v[28:29]
	v_pk_fma_f32 v[116:117], v[4:5], v[116:117], v[108:109]
	v_mul_f32_e32 v100, 0x3d372713, v104
	v_lshlrev_b32_e32 v108, 16, v101
	v_and_b32_e32 v109, 0xffff0000, v101
	v_mul_f32_e32 v101, 0x3d372713, v105
	v_mul_f32_e32 v100, v104, v100
	v_mul_f32_e32 v101, v105, v101
	v_fma_f32 v100, v104, v100, v104
	v_fma_f32 v101, v105, v101, v105
	v_mul_f32_e32 v100, 0x3f4c422a, v100
	v_mul_f32_e32 v101, 0x3f4c422a, v101
	v_add_f32_e32 v100, v100, v100
	v_add_f32_e32 v101, v101, v101
	v_mul_f32_e32 v100, 0xbfb8aa3b, v100
	v_mul_f32_e32 v101, 0xbfb8aa3b, v101
	v_exp_f32_e32 v100, v100
	v_exp_f32_e32 v101, v101
	v_pk_fma_f32 v[116:117], v[12:13], v[108:109], v[116:117]
	v_and_b32_e32 v119, 0xffff0000, v96
	v_add_f32_e32 v100, 1.0, v100
	v_add_f32_e32 v101, 1.0, v101
	v_rcp_f32_e32 v100, v100
	v_rcp_f32_e32 v101, v101
	v_pk_add_f32 v[116:117], v[116:117], v[16:17]
	v_pk_mul_f32 v[100:101], v[104:105], v[100:101]
	s_nop 0
	v_pk_mul_f32 v[104:105], v[116:117], v[100:101]
	v_cvt_pk_bf16_f32 v100, v106, v107
	v_cvt_pk_bf16_f32 v101, v102, v103
	v_cvt_pk_bf16_f32 v102, v114, v115
	v_cvt_pk_bf16_f32 v103, v104, v105
	v_mad_i64_i32 v[104:105], s[0:1], v168, s91, v[130:131]
	global_store_dwordx4 v[104:105], v[100:103], off sc1 nt
	s_nop 2
	v_pk_mul_f32 v[100:101], v[50:51], v[146:147]
	v_lshlrev_b32_e32 v106, 16, v90
	v_pk_fma_f32 v[100:101], v[38:39], v[148:149], v[100:101]
	v_and_b32_e32 v107, 0xffff0000, v90
	v_pk_fma_f32 v[100:101], v[58:59], v[136:137], v[100:101]
	v_pk_mul_f32 v[104:105], v[42:43], v[112:113]
	v_pk_add_f32 v[100:101], v[100:101], v[62:63]
	v_pk_fma_f32 v[104:105], v[34:35], v[126:127], v[104:105]
	v_mul_f32_e32 v94, 0x3d372713, v100
	v_mul_f32_e32 v90, 0x3d372713, v101
	v_mul_f32_e32 v94, v100, v94
	v_mul_f32_e32 v90, v101, v90
	v_fma_f32 v94, v100, v94, v100
	v_fma_f32 v90, v101, v90, v101
	v_mul_f32_e32 v94, 0x3f4c422a, v94
	v_mul_f32_e32 v90, 0x3f4c422a, v90
	v_add_f32_e32 v94, v94, v94
	v_add_f32_e32 v90, v90, v90
	v_mul_f32_e32 v94, 0xbfb8aa3b, v94
	v_mul_f32_e32 v90, 0xbfb8aa3b, v90
	v_exp_f32_e32 v94, v94
	v_exp_f32_e32 v90, v90
	v_lshlrev_b32_e32 v126, 16, v95
	v_and_b32_e32 v127, 0xffff0000, v95
	v_add_f32_e32 v94, 1.0, v94
	v_add_f32_e32 v90, 1.0, v90
	v_rcp_f32_e32 v102, v94
	v_rcp_f32_e32 v103, v90
	v_pk_fma_f32 v[104:105], v[46:47], v[106:107], v[104:105]
	v_pk_mul_f32 v[100:101], v[100:101], v[102:103]
	v_pk_mul_f32 v[102:103], v[52:53], v[134:135]
	v_pk_add_f32 v[104:105], v[104:105], v[54:55]
	v_pk_fma_f32 v[102:103], v[40:41], v[144:145], v[102:103]
	v_pk_mul_f32 v[100:101], v[104:105], v[100:101]
	v_pk_fma_f32 v[94:95], v[60:61], v[126:127], v[102:103]
	v_lshlrev_b32_e32 v104, 16, v91
	v_pk_add_f32 v[94:95], v[94:95], v[64:65]
	v_and_b32_e32 v105, 0xffff0000, v91
	v_mul_f32_e32 v90, 0x3d372713, v94
	v_mul_f32_e32 v91, 0x3d372713, v95
	v_mul_f32_e32 v90, v94, v90
	v_mul_f32_e32 v91, v95, v91
	v_fma_f32 v90, v94, v90, v94
	v_fma_f32 v91, v95, v91, v95
	v_mul_f32_e32 v90, 0x3f4c422a, v90
	v_mul_f32_e32 v91, 0x3f4c422a, v91
	v_add_f32_e32 v90, v90, v90
	v_add_f32_e32 v91, v91, v91
	v_mul_f32_e32 v90, 0xbfb8aa3b, v90
	v_mul_f32_e32 v91, 0xbfb8aa3b, v91
	v_exp_f32_e32 v90, v90
	v_exp_f32_e32 v91, v91
	v_pk_mul_f32 v[102:103], v[44:45], v[98:99]
	v_add_f32_e32 v90, 1.0, v90
	v_add_f32_e32 v91, 1.0, v91
	v_rcp_f32_e32 v90, v90
	v_rcp_f32_e32 v91, v91
	v_pk_fma_f32 v[102:103], v[36:37], v[124:125], v[102:103]
	v_pk_mul_f32 v[90:91], v[94:95], v[90:91]
	v_pk_fma_f32 v[102:103], v[48:49], v[104:105], v[102:103]
	s_nop 0
	v_pk_add_f32 v[102:103], v[102:103], v[56:57]
	s_nop 0
	v_pk_mul_f32 v[94:95], v[102:103], v[90:91]
	v_pk_mul_f32 v[90:91], v[30:31], v[132:133]
	s_nop 0
	v_pk_fma_f32 v[90:91], v[18:19], v[142:143], v[90:91]
	s_nop 0
	v_pk_fma_f32 v[90:91], v[22:23], v[118:119], v[90:91]
	s_nop 0
	v_pk_add_f32 v[102:103], v[90:91], v[26:27]
	s_nop 0
	v_mul_f32_e32 v90, 0x3d372713, v102
	v_mul_f32_e32 v90, v102, v90
	v_fma_f32 v90, v102, v90, v102
	v_mul_f32_e32 v90, 0x3f4c422a, v90
	v_add_f32_e32 v90, v90, v90
	v_mul_f32_e32 v90, 0xbfb8aa3b, v90
	v_exp_f32_e32 v90, v90
	s_nop 0
	v_add_f32_e32 v90, 1.0, v90
	v_rcp_f32_e32 v114, v90
	v_pk_mul_f32 v[90:91], v[6:7], v[110:111]
	s_nop 0
	v_pk_fma_f32 v[116:117], v[2:3], v[122:123], v[90:91]
	v_lshlrev_b32_e32 v90, 16, v92
	v_and_b32_e32 v91, 0xffff0000, v92
	v_mul_f32_e32 v92, 0x3d372713, v103
	v_mul_f32_e32 v92, v103, v92
	v_fma_f32 v92, v103, v92, v103
	v_mul_f32_e32 v92, 0x3f4c422a, v92
	v_add_f32_e32 v92, v92, v92
	v_mul_f32_e32 v92, 0xbfb8aa3b, v92
	v_exp_f32_e32 v92, v92
	v_pk_fma_f32 v[116:117], v[10:11], v[90:91], v[116:117]
	v_add_f32_e32 v92, 1.0, v92
	v_rcp_f32_e32 v115, v92
	v_pk_add_f32 v[116:117], v[116:117], v[14:15]
	v_pk_mul_f32 v[102:103], v[102:103], v[114:115]
	s_nop 0
	v_pk_mul_f32 v[114:115], v[116:117], v[102:103]
	v_pk_mul_f32 v[102:103], v[32:33], v[128:129]
	v_lshlrev_b32_e32 v116, 16, v97
	v_pk_fma_f32 v[102:103], v[20:21], v[140:141], v[102:103]
	v_and_b32_e32 v117, 0xffff0000, v97
	v_pk_fma_f32 v[96:97], v[24:25], v[116:117], v[102:103]
	v_pk_mul_f32 v[102:103], v[8:9], v[108:109]
	v_pk_add_f32 v[96:97], v[96:97], v[28:29]
	v_pk_fma_f32 v[120:121], v[4:5], v[120:121], v[102:103]
	v_mul_f32_e32 v92, 0x3d372713, v96
	v_lshlrev_b32_e32 v102, 16, v93
	v_and_b32_e32 v103, 0xffff0000, v93
	v_mul_f32_e32 v93, 0x3d372713, v97
	v_mul_f32_e32 v92, v96, v92
	v_mul_f32_e32 v93, v97, v93
	v_fma_f32 v92, v96, v92, v96
	v_fma_f32 v93, v97, v93, v97
; __device__ __forceinline__ unsigned cvtpk(float lo, float hi) { f32x2 v = {lo, hi}; bf16x2_t b = __builtin_convertvector(v, bf16x2_t); return __builtin_bit_cast(unsigned, b); }
; __device__ __forceinline__ float gelu_tanh(float x) { const float u = 0.7978845608028654f * (x + 0.044715f * x * x * x); return x * sigmoidf_(2.0f * u); }
; __device__ __forceinline__ void st16_wt(void* p, u32x4 v) { asm volatile("global_store_dwordx4 %0, %1, off sc1\n\ts_nop 2" :: "v"(p), "v"(v) : "memory"); }
; __device__ __forceinline__ float bfe(const u32x4& w, int e) { return (e & 1) ? __builtin_bit_cast(float, w[e >> 1] & 0xffff0000u) : __builtin_bit_cast(float, w[e >> 1] << 16); }
; __device__ __forceinline__ void conv_pass(const bf16_t* __restrict__ U, const float* __restrict__ cw, const float* __restrict__ cb, bf16_t* __restrict__ GA, int tg, int wv) {
;     ...
; #pragma unroll
;         for (int i = 0; i < RUN; ++i) {
;             float o[8];
; #pragma unroll
;             for (int e = 0; e < 8; ++e) {
;                 const float ua = bfe(ra[i], e) * wa[0][e >> 2][e & 3] + bfe(ra[i + 1], e) * wa[1][e >> 2][e & 3] + bfe(ra[i + 2], e) * wa[2][e >> 2][e & 3] + ba[e >> 2][e & 3];
;                 const float ub = bfe(rb[i], e) * wb[0][e >> 2][e & 3] + bfe(rb[i + 1], e) * wb[1][e >> 2][e & 3] + bfe(rb[i + 2], e) * wb[2][e >> 2][e & 3] + bb[e >> 2][e & 3];
;                 o[e] = gelu_tanh(ua) * ub;
;             }
;             u32x4 w; w.x = cvtpk(o[0], o[1]); w.y = cvtpk(o[2], o[3]); w.z = cvtpk(o[4], o[5]); w.w = cvtpk(o[6], o[7]);
;             st16_wt(GA + (size_t)(t0 + i) * DFF + c0, w);
	v_mul_f32_e32 v92, 0x3f4c422a, v92
	v_mul_f32_e32 v93, 0x3f4c422a, v93
	v_add_f32_e32 v92, v92, v92
	v_add_f32_e32 v93, v93, v93
	v_mul_f32_e32 v92, 0xbfb8aa3b, v92
	v_mul_f32_e32 v93, 0xbfb8aa3b, v93
	v_exp_f32_e32 v92, v92
	v_exp_f32_e32 v93, v93
	v_pk_fma_f32 v[120:121], v[12:13], v[102:103], v[120:121]
	v_add_f32_e32 v92, 1.0, v92
	v_add_f32_e32 v93, 1.0, v93
	v_rcp_f32_e32 v92, v92
	v_rcp_f32_e32 v93, v93
	v_pk_add_f32 v[120:121], v[120:121], v[16:17]
	v_pk_mul_f32 v[92:93], v[96:97], v[92:93]
	s_nop 0
	v_pk_mul_f32 v[96:97], v[120:121], v[92:93]
	v_cvt_pk_bf16_f32 v92, v100, v101
	v_cvt_pk_bf16_f32 v93, v94, v95
	v_cvt_pk_bf16_f32 v94, v114, v115
	v_cvt_pk_bf16_f32 v95, v96, v97
	v_mad_i64_i32 v[96:97], s[0:1], v167, s91, v[130:131]
	global_store_dwordx4 v[96:97], v[92:95], off sc1 nt
	s_nop 2
	v_pk_mul_f32 v[92:93], v[50:51], v[136:137]
	v_lshlrev_b32_e32 v120, 16, v86
	v_pk_fma_f32 v[92:93], v[38:39], v[146:147], v[92:93]
	v_and_b32_e32 v121, 0xffff0000, v86
	v_pk_fma_f32 v[92:93], v[58:59], v[120:121], v[92:93]
	v_lshlrev_b32_e32 v100, 16, v82
	v_pk_add_f32 v[92:93], v[92:93], v[62:63]
	v_and_b32_e32 v101, 0xffff0000, v82
	v_mul_f32_e32 v86, 0x3d372713, v92
	v_mul_f32_e32 v82, 0x3d372713, v93
	v_mul_f32_e32 v86, v92, v86
	v_mul_f32_e32 v82, v93, v82
	v_fma_f32 v86, v92, v86, v92
	v_fma_f32 v82, v93, v82, v93
	v_mul_f32_e32 v86, 0x3f4c422a, v86
	v_mul_f32_e32 v82, 0x3f4c422a, v82
	v_add_f32_e32 v86, v86, v86
	v_add_f32_e32 v82, v82, v82
	v_mul_f32_e32 v86, 0xbfb8aa3b, v86
	v_mul_f32_e32 v82, 0xbfb8aa3b, v82
	v_exp_f32_e32 v86, v86
	v_exp_f32_e32 v82, v82
	v_lshlrev_b32_e32 v114, 16, v87
	v_and_b32_e32 v115, 0xffff0000, v87
	v_add_f32_e32 v86, 1.0, v86
	v_add_f32_e32 v82, 1.0, v82
	v_rcp_f32_e32 v94, v86
	v_rcp_f32_e32 v95, v82
	v_pk_mul_f32 v[96:97], v[42:43], v[106:107]
	v_pk_mul_f32 v[92:93], v[92:93], v[94:95]
	v_pk_mul_f32 v[94:95], v[52:53], v[126:127]
	v_pk_fma_f32 v[96:97], v[34:35], v[112:113], v[96:97]
	v_pk_fma_f32 v[94:95], v[40:41], v[134:135], v[94:95]
	v_pk_fma_f32 v[96:97], v[46:47], v[100:101], v[96:97]
	v_pk_fma_f32 v[86:87], v[60:61], v[114:115], v[94:95]
	v_pk_mul_f32 v[94:95], v[44:45], v[104:105]
	v_pk_add_f32 v[86:87], v[86:87], v[64:65]
	v_pk_fma_f32 v[94:95], v[36:37], v[98:99], v[94:95]
	v_mul_f32_e32 v82, 0x3d372713, v86
	v_lshlrev_b32_e32 v98, 16, v83
	v_and_b32_e32 v99, 0xffff0000, v83
	v_mul_f32_e32 v83, 0x3d372713, v87
	v_mul_f32_e32 v82, v86, v82
	v_mul_f32_e32 v83, v87, v83
	v_fma_f32 v82, v86, v82, v86
	v_fma_f32 v83, v87, v83, v87
	v_mul_f32_e32 v82, 0x3f4c422a, v82
	v_mul_f32_e32 v83, 0x3f4c422a, v83
	v_add_f32_e32 v82, v82, v82
	v_add_f32_e32 v83, v83, v83
	v_mul_f32_e32 v82, 0xbfb8aa3b, v82
	v_mul_f32_e32 v83, 0xbfb8aa3b, v83
	v_exp_f32_e32 v82, v82
	v_exp_f32_e32 v83, v83
	v_pk_fma_f32 v[94:95], v[48:49], v[98:99], v[94:95]
	v_lshlrev_b32_e32 v112, 16, v88
	v_add_f32_e32 v82, 1.0, v82
	v_add_f32_e32 v83, 1.0, v83
	v_rcp_f32_e32 v82, v82
	v_rcp_f32_e32 v83, v83
	v_pk_add_f32 v[94:95], v[94:95], v[56:57]
	v_and_b32_e32 v113, 0xffff0000, v88
	v_pk_add_f32 v[96:97], v[96:97], v[54:55]
	v_pk_mul_f32 v[82:83], v[86:87], v[82:83]
	v_pk_mul_f32 v[92:93], v[96:97], v[92:93]
	v_pk_mul_f32 v[86:87], v[94:95], v[82:83]
	v_pk_mul_f32 v[82:83], v[30:31], v[118:119]
	v_pk_mul_f32 v[96:97], v[6:7], v[90:91]
	v_pk_fma_f32 v[82:83], v[18:19], v[132:133], v[82:83]
	v_pk_fma_f32 v[110:111], v[2:3], v[110:111], v[96:97]
	v_pk_fma_f32 v[82:83], v[22:23], v[112:113], v[82:83]
	v_lshlrev_b32_e32 v96, 16, v84
	v_pk_add_f32 v[82:83], v[82:83], v[26:27]
	v_and_b32_e32 v97, 0xffff0000, v84
	v_mul_f32_e32 v88, 0x3d372713, v82
	v_mul_f32_e32 v84, 0x3d372713, v83
	v_mul_f32_e32 v88, v82, v88
	v_mul_f32_e32 v84, v83, v84
	v_fma_f32 v88, v82, v88, v82
	v_fma_f32 v84, v83, v84, v83
	v_mul_f32_e32 v88, 0x3f4c422a, v88
	v_mul_f32_e32 v84, 0x3f4c422a, v84
	v_add_f32_e32 v88, v88, v88
	v_add_f32_e32 v84, v84, v84
	v_mul_f32_e32 v88, 0xbfb8aa3b, v88
	v_mul_f32_e32 v84, 0xbfb8aa3b, v84
	v_exp_f32_e32 v88, v88
	v_exp_f32_e32 v84, v84
	v_pk_fma_f32 v[110:111], v[10:11], v[96:97], v[110:111]
	v_add_f32_e32 v88, 1.0, v88
	v_add_f32_e32 v84, 1.0, v84
	v_rcp_f32_e32 v94, v88
	v_rcp_f32_e32 v95, v84
	v_pk_add_f32 v[110:111], v[110:111], v[14:15]
	v_pk_mul_f32 v[82:83], v[82:83], v[94:95]
	s_nop 0
	v_pk_mul_f32 v[122:123], v[110:111], v[82:83]
	v_pk_mul_f32 v[82:83], v[32:33], v[116:117]
	v_lshlrev_b32_e32 v110, 16, v89
	v_pk_fma_f32 v[82:83], v[20:21], v[128:129], v[82:83]
	v_and_b32_e32 v111, 0xffff0000, v89
	v_pk_fma_f32 v[82:83], v[24:25], v[110:111], v[82:83]
	v_lshlrev_b32_e32 v94, 16, v85
	v_pk_add_f32 v[82:83], v[82:83], v[28:29]
	v_and_b32_e32 v95, 0xffff0000, v85
	v_mul_f32_e32 v84, 0x3d372713, v82
	v_mul_f32_e32 v85, 0x3d372713, v83
	v_mul_f32_e32 v84, v82, v84
	v_mul_f32_e32 v85, v83, v85
	v_fma_f32 v84, v82, v84, v82
	v_fma_f32 v85, v83, v85, v83
	v_mul_f32_e32 v84, 0x3f4c422a, v84
	v_mul_f32_e32 v85, 0x3f4c422a, v85
	v_add_f32_e32 v84, v84, v84
	v_add_f32_e32 v85, v85, v85
	v_mul_f32_e32 v84, 0xbfb8aa3b, v84
	v_mul_f32_e32 v85, 0xbfb8aa3b, v85
	v_exp_f32_e32 v84, v84
	v_exp_f32_e32 v85, v85
	v_pk_mul_f32 v[88:89], v[8:9], v[102:103]
	v_add_f32_e32 v84, 1.0, v84
	v_add_f32_e32 v85, 1.0, v85
	v_rcp_f32_e32 v84, v84
	v_rcp_f32_e32 v85, v85
	v_pk_fma_f32 v[88:89], v[4:5], v[108:109], v[88:89]
	v_pk_mul_f32 v[108:109], v[6:7], v[96:97]
	v_pk_fma_f32 v[88:89], v[12:13], v[94:95], v[88:89]
	v_pk_mul_f32 v[82:83], v[82:83], v[84:85]
	v_pk_add_f32 v[88:89], v[88:89], v[16:17]
	v_cvt_pk_bf16_f32 v84, v122, v123
	v_pk_mul_f32 v[88:89], v[88:89], v[82:83]
	v_cvt_pk_bf16_f32 v82, v92, v93
	v_cvt_pk_bf16_f32 v83, v86, v87
; __device__ __forceinline__ unsigned cvtpk(float lo, float hi) { f32x2 v = {lo, hi}; bf16x2_t b = __builtin_convertvector(v, bf16x2_t); return __builtin_bit_cast(unsigned, b); }
; __device__ __forceinline__ float gelu_tanh(float x) { const float u = 0.7978845608028654f * (x + 0.044715f * x * x * x); return x * sigmoidf_(2.0f * u); }
; __device__ __forceinline__ void st16_wt(void* p, u32x4 v) { asm volatile("global_store_dwordx4 %0, %1, off sc1\n\ts_nop 2" :: "v"(p), "v"(v) : "memory"); }
; __device__ __forceinline__ float bfe(const u32x4& w, int e) { return (e & 1) ? __builtin_bit_cast(float, w[e >> 1] & 0xffff0000u) : __builtin_bit_cast(float, w[e >> 1] << 16); }
; __device__ __forceinline__ void conv_pass(const bf16_t* __restrict__ U, const float* __restrict__ cw, const float* __restrict__ cb, bf16_t* __restrict__ GA, int tg, int wv) {
;     ...
; #pragma unroll
;         for (int i = 0; i < RUN; ++i) {
;             float o[8];
; #pragma unroll
;             for (int e = 0; e < 8; ++e) {
;                 const float ua = bfe(ra[i], e) * wa[0][e >> 2][e & 3] + bfe(ra[i + 1], e) * wa[1][e >> 2][e & 3] + bfe(ra[i + 2], e) * wa[2][e >> 2][e & 3] + ba[e >> 2][e & 3];
;                 const float ub = bfe(rb[i], e) * wb[0][e >> 2][e & 3] + bfe(rb[i + 1], e) * wb[1][e >> 2][e & 3] + bfe(rb[i + 2], e) * wb[2][e >> 2][e & 3] + bb[e >> 2][e & 3];
;                 o[e] = gelu_tanh(ua) * ub;
;             }
;             u32x4 w; w.x = cvtpk(o[0], o[1]); w.y = cvtpk(o[2], o[3]); w.z = cvtpk(o[4], o[5]); w.w = cvtpk(o[6], o[7]);
;             st16_wt(GA + (size_t)(t0 + i) * DFF + c0, w);
	v_cvt_pk_bf16_f32 v85, v88, v89
	v_mad_i64_i32 v[86:87], s[0:1], v166, s91, v[130:131]
	global_store_dwordx4 v[86:87], v[82:85], off sc1 nt
	s_nop 2
	v_pk_mul_f32 v[82:83], v[50:51], v[120:121]
	v_lshlrev_b32_e32 v86, 16, v78
	v_pk_fma_f32 v[82:83], v[38:39], v[136:137], v[82:83]
	v_and_b32_e32 v87, 0xffff0000, v78
	v_pk_fma_f32 v[82:83], v[58:59], v[86:87], v[82:83]
	v_pk_fma_f32 v[108:109], v[2:3], v[90:91], v[108:109]
	v_pk_add_f32 v[84:85], v[82:83], v[62:63]
	v_pk_mul_f32 v[82:83], v[42:43], v[100:101]
	v_mul_f32_e32 v78, 0x3d372713, v84
	v_pk_fma_f32 v[92:93], v[34:35], v[106:107], v[82:83]
	v_lshlrev_b32_e32 v82, 16, v74
	v_and_b32_e32 v83, 0xffff0000, v74
	v_mul_f32_e32 v74, 0x3d372713, v85
	v_mul_f32_e32 v78, v84, v78
	v_mul_f32_e32 v74, v85, v74
	v_fma_f32 v78, v84, v78, v84
	v_fma_f32 v74, v85, v74, v85
	v_mul_f32_e32 v78, 0x3f4c422a, v78
	v_mul_f32_e32 v74, 0x3f4c422a, v74
	v_add_f32_e32 v78, v78, v78
	v_add_f32_e32 v74, v74, v74
	v_mul_f32_e32 v78, 0xbfb8aa3b, v78
	v_mul_f32_e32 v74, 0xbfb8aa3b, v74
	v_exp_f32_e32 v78, v78
	v_exp_f32_e32 v74, v74
	v_pk_fma_f32 v[92:93], v[46:47], v[82:83], v[92:93]
	v_lshlrev_b32_e32 v90, 16, v76
	v_add_f32_e32 v78, 1.0, v78
	v_add_f32_e32 v74, 1.0, v74
	v_rcp_f32_e32 v88, v78
	v_rcp_f32_e32 v89, v74
	v_pk_add_f32 v[92:93], v[92:93], v[54:55]
	v_and_b32_e32 v91, 0xffff0000, v76
	v_pk_fma_f32 v[108:109], v[10:11], v[90:91], v[108:109]
	v_pk_mul_f32 v[84:85], v[84:85], v[88:89]
	v_lshlrev_b32_e32 v88, 16, v79
	v_pk_mul_f32 v[106:107], v[92:93], v[84:85]
	v_pk_mul_f32 v[84:85], v[52:53], v[114:115]
	v_and_b32_e32 v89, 0xffff0000, v79
	v_pk_fma_f32 v[84:85], v[40:41], v[126:127], v[84:85]
	v_pk_add_f32 v[108:109], v[108:109], v[14:15]
	v_pk_fma_f32 v[78:79], v[60:61], v[88:89], v[84:85]
	v_pk_mul_f32 v[84:85], v[44:45], v[98:99]
	v_pk_add_f32 v[78:79], v[78:79], v[64:65]
	v_pk_fma_f32 v[92:93], v[36:37], v[104:105], v[84:85]
	v_mul_f32_e32 v74, 0x3d372713, v78
	v_lshlrev_b32_e32 v84, 16, v75
	v_and_b32_e32 v85, 0xffff0000, v75
	v_mul_f32_e32 v75, 0x3d372713, v79
	v_mul_f32_e32 v74, v78, v74
	v_mul_f32_e32 v75, v79, v75
	v_fma_f32 v74, v78, v74, v78
	v_fma_f32 v75, v79, v75, v79
	v_mul_f32_e32 v74, 0x3f4c422a, v74
	v_mul_f32_e32 v75, 0x3f4c422a, v75
	v_add_f32_e32 v74, v74, v74
	v_add_f32_e32 v75, v75, v75
	v_mul_f32_e32 v74, 0xbfb8aa3b, v74
	v_mul_f32_e32 v75, 0xbfb8aa3b, v75
	v_exp_f32_e32 v74, v74
	v_exp_f32_e32 v75, v75
	v_pk_fma_f32 v[92:93], v[48:49], v[84:85], v[92:93]
	v_add_f32_e32 v74, 1.0, v74
	v_add_f32_e32 v75, 1.0, v75
	v_rcp_f32_e32 v74, v74
	v_rcp_f32_e32 v75, v75
	v_pk_add_f32 v[92:93], v[92:93], v[56:57]
	v_pk_mul_f32 v[74:75], v[78:79], v[74:75]
	s_nop 0
	v_pk_mul_f32 v[104:105], v[92:93], v[74:75]
	v_pk_mul_f32 v[74:75], v[30:31], v[112:113]
	v_lshlrev_b32_e32 v92, 16, v80
	v_pk_fma_f32 v[74:75], v[18:19], v[118:119], v[74:75]
	v_and_b32_e32 v93, 0xffff0000, v80
	v_pk_fma_f32 v[74:75], v[22:23], v[92:93], v[74:75]
	s_nop 0
	v_pk_add_f32 v[74:75], v[74:75], v[26:27]
	s_nop 0
	v_mul_f32_e32 v78, 0x3d372713, v74
	v_mul_f32_e32 v76, 0x3d372713, v75
	v_mul_f32_e32 v78, v74, v78
	v_mul_f32_e32 v76, v75, v76
	v_fma_f32 v78, v74, v78, v74
	v_fma_f32 v76, v75, v76, v75
	v_mul_f32_e32 v78, 0x3f4c422a, v78
	v_mul_f32_e32 v76, 0x3f4c422a, v76
	v_add_f32_e32 v78, v78, v78
	v_add_f32_e32 v76, v76, v76
	v_mul_f32_e32 v78, 0xbfb8aa3b, v78
	v_mul_f32_e32 v76, 0xbfb8aa3b, v76
	v_exp_f32_e32 v78, v78
	v_exp_f32_e32 v76, v76
	v_add_f32_e32 v78, 1.0, v78
	v_add_f32_e32 v76, 1.0, v76
	v_rcp_f32_e32 v78, v78
	v_rcp_f32_e32 v79, v76
	s_nop 0
	v_pk_mul_f32 v[74:75], v[74:75], v[78:79]
	s_nop 0
	v_pk_mul_f32 v[108:109], v[108:109], v[74:75]
	v_pk_mul_f32 v[74:75], v[32:33], v[110:111]
	v_lshlrev_b32_e32 v78, 16, v81
	v_pk_fma_f32 v[74:75], v[20:21], v[116:117], v[74:75]
	v_and_b32_e32 v79, 0xffff0000, v81
	v_pk_fma_f32 v[74:75], v[24:25], v[78:79], v[74:75]
	s_nop 0
	v_pk_add_f32 v[80:81], v[74:75], v[28:29]
	s_nop 0
	v_mul_f32_e32 v74, 0x3d372713, v80
	v_mul_f32_e32 v74, v80, v74
	v_fma_f32 v74, v80, v74, v80
	v_mul_f32_e32 v74, 0x3f4c422a, v74
	v_add_f32_e32 v74, v74, v74
	v_mul_f32_e32 v74, 0xbfb8aa3b, v74
	v_exp_f32_e32 v74, v74
	s_nop 0
	v_add_f32_e32 v74, 1.0, v74
	v_rcp_f32_e32 v76, v74
	v_pk_mul_f32 v[74:75], v[8:9], v[94:95]
	s_nop 0
	v_pk_fma_f32 v[102:103], v[4:5], v[102:103], v[74:75]
	v_lshlrev_b32_e32 v74, 16, v77
	v_and_b32_e32 v75, 0xffff0000, v77
	v_mul_f32_e32 v77, 0x3d372713, v81
	v_mul_f32_e32 v77, v81, v77
	v_fma_f32 v77, v81, v77, v81
	v_mul_f32_e32 v77, 0x3f4c422a, v77
	v_add_f32_e32 v77, v77, v77
	v_mul_f32_e32 v77, 0xbfb8aa3b, v77
	v_exp_f32_e32 v77, v77
	v_pk_fma_f32 v[102:103], v[12:13], v[74:75], v[102:103]
	v_add_f32_e32 v77, 1.0, v77
	v_rcp_f32_e32 v77, v77
	v_pk_add_f32 v[102:103], v[102:103], v[16:17]
	v_pk_mul_f32 v[76:77], v[80:81], v[76:77]
	s_nop 0
	v_pk_mul_f32 v[76:77], v[102:103], v[76:77]
	v_cvt_pk_bf16_f32 v103, v104, v105
	v_cvt_pk_bf16_f32 v105, v76, v77
	v_mad_i64_i32 v[76:77], s[0:1], v165, s91, v[130:131]
	v_cvt_pk_bf16_f32 v102, v106, v107
	v_cvt_pk_bf16_f32 v104, v108, v109
	global_store_dwordx4 v[76:77], v[102:105], off sc1 nt
	s_nop 2
	v_pk_mul_f32 v[76:77], v[50:51], v[86:87]
	v_lshlrev_b32_e32 v80, 16, v70
	v_pk_fma_f32 v[76:77], v[38:39], v[120:121], v[76:77]
	v_and_b32_e32 v81, 0xffff0000, v70
	v_pk_fma_f32 v[76:77], v[58:59], v[80:81], v[76:77]
	v_pk_mul_f32 v[106:107], v[44:45], v[84:85]
	v_pk_add_f32 v[102:103], v[76:77], v[62:63]
	v_pk_mul_f32 v[76:77], v[42:43], v[82:83]
	v_mul_f32_e32 v70, 0x3d372713, v102
	v_pk_fma_f32 v[100:101], v[34:35], v[100:101], v[76:77]
	v_lshlrev_b32_e32 v76, 16, v66
	v_and_b32_e32 v77, 0xffff0000, v66
; __device__ __forceinline__ unsigned cvtpk(float lo, float hi) { f32x2 v = {lo, hi}; bf16x2_t b = __builtin_convertvector(v, bf16x2_t); return __builtin_bit_cast(unsigned, b); }
; __device__ __forceinline__ float gelu_tanh(float x) { const float u = 0.7978845608028654f * (x + 0.044715f * x * x * x); return x * sigmoidf_(2.0f * u); }
; __device__ __forceinline__ void st16_wt(void* p, u32x4 v) { asm volatile("global_store_dwordx4 %0, %1, off sc1\n\ts_nop 2" :: "v"(p), "v"(v) : "memory"); }
; __device__ __forceinline__ float bfe(const u32x4& w, int e) { return (e & 1) ? __builtin_bit_cast(float, w[e >> 1] & 0xffff0000u) : __builtin_bit_cast(float, w[e >> 1] << 16); }
; __device__ __forceinline__ void conv_pass(const bf16_t* __restrict__ U, const float* __restrict__ cw, const float* __restrict__ cb, bf16_t* __restrict__ GA, int tg, int wv) {
;     ...
; #pragma unroll
;         for (int i = 0; i < RUN; ++i) {
;             float o[8];
; #pragma unroll
;             for (int e = 0; e < 8; ++e) {
;                 const float ua = bfe(ra[i], e) * wa[0][e >> 2][e & 3] + bfe(ra[i + 1], e) * wa[1][e >> 2][e & 3] + bfe(ra[i + 2], e) * wa[2][e >> 2][e & 3] + ba[e >> 2][e & 3];
;                 const float ub = bfe(rb[i], e) * wb[0][e >> 2][e & 3] + bfe(rb[i + 1], e) * wb[1][e >> 2][e & 3] + bfe(rb[i + 2], e) * wb[2][e >> 2][e & 3] + bb[e >> 2][e & 3];
;                 o[e] = gelu_tanh(ua) * ub;
;             }
;             u32x4 w; w.x = cvtpk(o[0], o[1]); w.y = cvtpk(o[2], o[3]); w.z = cvtpk(o[4], o[5]); w.w = cvtpk(o[6], o[7]);
;             st16_wt(GA + (size_t)(t0 + i) * DFF + c0, w);
	v_mul_f32_e32 v66, 0x3d372713, v103
	v_mul_f32_e32 v70, v102, v70
	v_mul_f32_e32 v66, v103, v66
	v_fma_f32 v70, v102, v70, v102
	v_fma_f32 v66, v103, v66, v103
	v_mul_f32_e32 v70, 0x3f4c422a, v70
	v_mul_f32_e32 v66, 0x3f4c422a, v66
	v_add_f32_e32 v70, v70, v70
	v_add_f32_e32 v66, v66, v66
	v_mul_f32_e32 v70, 0xbfb8aa3b, v70
	v_mul_f32_e32 v66, 0xbfb8aa3b, v66
	v_exp_f32_e32 v70, v70
	v_exp_f32_e32 v66, v66
	v_pk_fma_f32 v[100:101], v[46:47], v[76:77], v[100:101]
	v_pk_fma_f32 v[98:99], v[36:37], v[98:99], v[106:107]
	v_add_f32_e32 v70, 1.0, v70
	v_add_f32_e32 v66, 1.0, v66
	v_rcp_f32_e32 v104, v70
	v_rcp_f32_e32 v105, v66
	v_pk_add_f32 v[100:101], v[100:101], v[54:55]
	v_pk_mul_f32 v[108:109], v[6:7], v[90:91]
	v_pk_mul_f32 v[50:51], v[50:51], v[80:81]
	v_pk_mul_f32 v[102:103], v[102:103], v[104:105]
	v_pk_fma_f32 v[108:109], v[2:3], v[96:97], v[108:109]
	v_pk_mul_f32 v[102:103], v[100:101], v[102:103]
	v_pk_mul_f32 v[100:101], v[52:53], v[88:89]
	v_lshlrev_b32_e32 v96, 16, v68
	v_pk_fma_f32 v[104:105], v[40:41], v[114:115], v[100:101]
	v_lshlrev_b32_e32 v100, 16, v71
	v_and_b32_e32 v101, 0xffff0000, v71
	v_pk_fma_f32 v[70:71], v[60:61], v[100:101], v[104:105]
	v_and_b32_e32 v97, 0xffff0000, v68
	v_pk_add_f32 v[70:71], v[70:71], v[64:65]
	v_pk_fma_f32 v[38:39], v[38:39], v[86:87], v[50:51]
	v_mul_f32_e32 v66, 0x3d372713, v70
	v_mul_f32_e32 v105, 0x3d372713, v71
	v_mul_f32_e32 v66, v70, v66
	v_mul_f32_e32 v105, v71, v105
	v_fma_f32 v66, v70, v66, v70
	v_fma_f32 v105, v71, v105, v71
	v_mul_f32_e32 v66, 0x3f4c422a, v66
	v_mul_f32_e32 v105, 0x3f4c422a, v105
	v_add_f32_e32 v66, v66, v66
	v_add_f32_e32 v105, v105, v105
	v_mul_f32_e32 v66, 0xbfb8aa3b, v66
	v_mul_f32_e32 v105, 0xbfb8aa3b, v105
	v_exp_f32_e32 v66, v66
	v_exp_f32_e32 v105, v105
	v_lshlrev_b32_e32 v50, 16, v164
	v_and_b32_e32 v51, 0xffff0000, v164
	v_add_f32_e32 v66, 1.0, v66
	v_add_f32_e32 v105, 1.0, v105
	v_rcp_f32_e32 v104, v66
	v_rcp_f32_e32 v105, v105
	v_lshlrev_b32_e32 v66, 16, v67
	v_and_b32_e32 v67, 0xffff0000, v67
	v_pk_fma_f32 v[98:99], v[48:49], v[66:67], v[98:99]
	v_pk_mul_f32 v[70:71], v[70:71], v[104:105]
	v_pk_add_f32 v[98:99], v[98:99], v[56:57]
	v_pk_fma_f32 v[38:39], v[58:59], v[50:51], v[38:39]
	v_pk_mul_f32 v[104:105], v[98:99], v[70:71]
	v_pk_mul_f32 v[70:71], v[30:31], v[92:93]
	v_lshlrev_b32_e32 v98, 16, v72
	v_pk_fma_f32 v[70:71], v[18:19], v[112:113], v[70:71]
	v_and_b32_e32 v99, 0xffff0000, v72
	v_pk_fma_f32 v[70:71], v[22:23], v[98:99], v[70:71]
	v_pk_mul_f32 v[30:31], v[30:31], v[98:99]
	v_pk_add_f32 v[70:71], v[70:71], v[26:27]
	v_pk_fma_f32 v[18:19], v[18:19], v[92:93], v[30:31]
	v_mul_f32_e32 v72, 0x3d372713, v70
	v_mul_f32_e32 v68, 0x3d372713, v71
	v_mul_f32_e32 v72, v70, v72
	v_mul_f32_e32 v68, v71, v68
	v_fma_f32 v72, v70, v72, v70
	v_fma_f32 v68, v71, v68, v71
	v_mul_f32_e32 v72, 0x3f4c422a, v72
	v_mul_f32_e32 v68, 0x3f4c422a, v68
	v_add_f32_e32 v72, v72, v72
	v_add_f32_e32 v68, v68, v68
	v_mul_f32_e32 v72, 0xbfb8aa3b, v72
	v_mul_f32_e32 v68, 0xbfb8aa3b, v68
	v_exp_f32_e32 v72, v72
	v_exp_f32_e32 v68, v68
	v_lshlrev_b32_e32 v30, 16, v159
	v_and_b32_e32 v31, 0xffff0000, v159
	v_add_f32_e32 v72, 1.0, v72
	v_add_f32_e32 v68, 1.0, v68
	v_rcp_f32_e32 v106, v72
	v_rcp_f32_e32 v107, v68
	v_pk_mul_f32 v[42:43], v[42:43], v[76:77]
	v_pk_fma_f32 v[18:19], v[22:23], v[30:31], v[18:19]
	v_pk_mul_f32 v[6:7], v[6:7], v[96:97]
	v_pk_add_f32 v[38:39], v[38:39], v[62:63]
	v_pk_fma_f32 v[34:35], v[34:35], v[82:83], v[42:43]
	v_lshlrev_b32_e32 v42, 16, v162
	v_and_b32_e32 v43, 0xffff0000, v162
	v_pk_add_f32 v[18:19], v[18:19], v[26:27]
	v_pk_fma_f32 v[2:3], v[2:3], v[90:91], v[6:7]
	v_lshlrev_b32_e32 v6, 16, v158
	v_and_b32_e32 v7, 0xffff0000, v158
	v_pk_fma_f32 v[108:109], v[10:11], v[96:97], v[108:109]
	v_mul_f32_e32 v50, 0x3d372713, v38
	v_pk_fma_f32 v[34:35], v[46:47], v[42:43], v[34:35]
	v_mul_f32_e32 v42, 0x3d372713, v39
	v_mul_f32_e32 v22, 0x3d372713, v18
	v_pk_fma_f32 v[2:3], v[10:11], v[6:7], v[2:3]
	v_mul_f32_e32 v6, 0x3d372713, v19
	v_pk_add_f32 v[108:109], v[108:109], v[14:15]
	v_pk_mul_f32 v[70:71], v[70:71], v[106:107]
	v_mul_f32_e32 v50, v38, v50
	v_mul_f32_e32 v42, v39, v42
	v_mul_f32_e32 v22, v18, v22
	v_mul_f32_e32 v6, v19, v6
	v_pk_mul_f32 v[106:107], v[108:109], v[70:71]
	v_pk_mul_f32 v[70:71], v[32:33], v[78:79]
	v_fma_f32 v50, v38, v50, v38
	v_fma_f32 v42, v39, v42, v39
	v_fma_f32 v22, v18, v22, v18
	v_fma_f32 v6, v19, v6, v19
	v_pk_fma_f32 v[108:109], v[20:21], v[110:111], v[70:71]
	v_lshlrev_b32_e32 v70, 16, v73
	v_and_b32_e32 v71, 0xffff0000, v73
	v_mul_f32_e32 v50, 0x3f4c422a, v50
	v_mul_f32_e32 v42, 0x3f4c422a, v42
	v_mul_f32_e32 v22, 0x3f4c422a, v22
; __device__ __forceinline__ unsigned cvtpk(float lo, float hi) { f32x2 v = {lo, hi}; bf16x2_t b = __builtin_convertvector(v, bf16x2_t); return __builtin_bit_cast(unsigned, b); }
; __device__ __forceinline__ float gelu_tanh(float x) { const float u = 0.7978845608028654f * (x + 0.044715f * x * x * x); return x * sigmoidf_(2.0f * u); }
; __device__ __forceinline__ void st16_wt(void* p, u32x4 v) { asm volatile("global_store_dwordx4 %0, %1, off sc1\n\ts_nop 2" :: "v"(p), "v"(v) : "memory"); }
; __device__ __forceinline__ float bfe(const u32x4& w, int e) { return (e & 1) ? __builtin_bit_cast(float, w[e >> 1] & 0xffff0000u) : __builtin_bit_cast(float, w[e >> 1] << 16); }
; __device__ __forceinline__ void conv_pass(const bf16_t* __restrict__ U, const float* __restrict__ cw, const float* __restrict__ cb, bf16_t* __restrict__ GA, int tg, int wv) {
;     ...
; #pragma unroll
;         for (int i = 0; i < RUN; ++i) {
;             float o[8];
; #pragma unroll
;             for (int e = 0; e < 8; ++e) {
;                 const float ua = bfe(ra[i], e) * wa[0][e >> 2][e & 3] + bfe(ra[i + 1], e) * wa[1][e >> 2][e & 3] + bfe(ra[i + 2], e) * wa[2][e >> 2][e & 3] + ba[e >> 2][e & 3];
;                 const float ub = bfe(rb[i], e) * wb[0][e >> 2][e & 3] + bfe(rb[i + 1], e) * wb[1][e >> 2][e & 3] + bfe(rb[i + 2], e) * wb[2][e >> 2][e & 3] + bb[e >> 2][e & 3];
;                 o[e] = gelu_tanh(ua) * ub;
;             }
;             u32x4 w; w.x = cvtpk(o[0], o[1]); w.y = cvtpk(o[2], o[3]); w.z = cvtpk(o[4], o[5]); w.w = cvtpk(o[6], o[7]);
;             st16_wt(GA + (size_t)(t0 + i) * DFF + c0, w);
;         }
;     }
	v_mul_f32_e32 v6, 0x3f4c422a, v6
	v_pk_fma_f32 v[72:73], v[24:25], v[70:71], v[108:109]
	v_add_f32_e32 v50, v50, v50
	v_add_f32_e32 v42, v42, v42
	v_add_f32_e32 v22, v22, v22
	v_add_f32_e32 v6, v6, v6
	v_pk_add_f32 v[72:73], v[72:73], v[28:29]
	v_mul_f32_e32 v50, 0xbfb8aa3b, v50
	v_mul_f32_e32 v42, 0xbfb8aa3b, v42
	v_mul_f32_e32 v22, 0xbfb8aa3b, v22
	v_mul_f32_e32 v6, 0xbfb8aa3b, v6
	v_mul_f32_e32 v68, 0x3d372713, v72
	v_exp_f32_e32 v50, v50
	v_exp_f32_e32 v42, v42
	v_exp_f32_e32 v22, v22
	v_exp_f32_e32 v6, v6
	v_mul_f32_e32 v68, v72, v68
	v_fma_f32 v68, v72, v68, v72
	v_mul_f32_e32 v68, 0x3f4c422a, v68
	v_add_f32_e32 v68, v68, v68
	v_add_f32_e32 v50, 1.0, v50
	v_add_f32_e32 v42, 1.0, v42
	v_add_f32_e32 v22, 1.0, v22
	v_add_f32_e32 v6, 1.0, v6
	v_mul_f32_e32 v68, 0xbfb8aa3b, v68
	v_rcp_f32_e32 v50, v50
	v_rcp_f32_e32 v51, v42
	v_rcp_f32_e32 v22, v22
	v_rcp_f32_e32 v23, v6
	v_exp_f32_e32 v68, v68
	v_pk_add_f32 v[34:35], v[34:35], v[54:55]
	v_pk_mul_f32 v[38:39], v[38:39], v[50:51]
	v_pk_add_f32 v[2:3], v[2:3], v[14:15]
	v_pk_mul_f32 v[6:7], v[18:19], v[22:23]
	v_add_f32_e32 v68, 1.0, v68
	v_pk_mul_f32 v[34:35], v[34:35], v[38:39]
	v_pk_mul_f32 v[38:39], v[52:53], v[100:101]
	v_pk_mul_f32 v[2:3], v[2:3], v[6:7]
	v_pk_mul_f32 v[6:7], v[32:33], v[70:71]
	v_rcp_f32_e32 v108, v68
	v_lshlrev_b32_e32 v68, 16, v69
	v_and_b32_e32 v69, 0xffff0000, v69
	v_pk_fma_f32 v[38:39], v[40:41], v[88:89], v[38:39]
	v_lshlrev_b32_e32 v40, 16, v161
	v_and_b32_e32 v41, 0xffff0000, v161
	v_pk_fma_f32 v[6:7], v[20:21], v[78:79], v[6:7]
	v_lshlrev_b32_e32 v10, 16, v157
	v_and_b32_e32 v11, 0xffff0000, v157
	v_pk_mul_f32 v[110:111], v[8:9], v[74:75]
	v_pk_fma_f32 v[38:39], v[60:61], v[40:41], v[38:39]
	v_pk_fma_f32 v[6:7], v[24:25], v[10:11], v[6:7]
	v_pk_mul_f32 v[8:9], v[8:9], v[68:69]
	v_pk_fma_f32 v[94:95], v[4:5], v[94:95], v[110:111]
	v_mul_f32_e32 v109, 0x3d372713, v73
	v_pk_add_f32 v[38:39], v[38:39], v[64:65]
	v_pk_add_f32 v[6:7], v[6:7], v[28:29]
	v_pk_fma_f32 v[4:5], v[4:5], v[74:75], v[8:9]
	v_lshlrev_b32_e32 v8, 16, v156
	v_and_b32_e32 v9, 0xffff0000, v156
	v_mul_f32_e32 v109, v73, v109
	v_mul_f32_e32 v40, 0x3d372713, v38
	v_mul_f32_e32 v41, 0x3d372713, v39
	v_mul_f32_e32 v10, 0x3d372713, v6
	v_pk_fma_f32 v[4:5], v[12:13], v[8:9], v[4:5]
	v_mul_f32_e32 v8, 0x3d372713, v7
	v_fma_f32 v109, v73, v109, v73
	v_mul_f32_e32 v40, v38, v40
	v_mul_f32_e32 v41, v39, v41
	v_mul_f32_e32 v10, v6, v10
	v_mul_f32_e32 v8, v7, v8
	v_mul_f32_e32 v109, 0x3f4c422a, v109
	v_fma_f32 v40, v38, v40, v38
	v_fma_f32 v41, v39, v41, v39
	v_fma_f32 v10, v6, v10, v6
	v_fma_f32 v8, v7, v8, v7
	v_add_f32_e32 v109, v109, v109
	v_mul_f32_e32 v40, 0x3f4c422a, v40
	v_mul_f32_e32 v41, 0x3f4c422a, v41
	v_mul_f32_e32 v10, 0x3f4c422a, v10
	v_mul_f32_e32 v8, 0x3f4c422a, v8
	v_mul_f32_e32 v109, 0xbfb8aa3b, v109
	v_add_f32_e32 v40, v40, v40
	v_add_f32_e32 v41, v41, v41
	v_add_f32_e32 v10, v10, v10
	v_add_f32_e32 v8, v8, v8
	v_exp_f32_e32 v109, v109
	v_mul_f32_e32 v40, 0xbfb8aa3b, v40
	v_mul_f32_e32 v41, 0xbfb8aa3b, v41
	v_mul_f32_e32 v10, 0xbfb8aa3b, v10
	v_mul_f32_e32 v8, 0xbfb8aa3b, v8
	v_exp_f32_e32 v40, v40
	v_exp_f32_e32 v41, v41
	v_exp_f32_e32 v10, v10
	v_exp_f32_e32 v8, v8
	v_add_f32_e32 v109, 1.0, v109
	v_rcp_f32_e32 v109, v109
	v_add_f32_e32 v40, 1.0, v40
	v_add_f32_e32 v41, 1.0, v41
	v_add_f32_e32 v10, 1.0, v10
	v_add_f32_e32 v8, 1.0, v8
	v_rcp_f32_e32 v40, v40
	v_rcp_f32_e32 v41, v41
	v_rcp_f32_e32 v10, v10
	v_rcp_f32_e32 v11, v8
	v_pk_mul_f32 v[42:43], v[44:45], v[66:67]
	v_pk_fma_f32 v[94:95], v[12:13], v[68:69], v[94:95]
	v_pk_fma_f32 v[36:37], v[36:37], v[84:85], v[42:43]
	v_lshlrev_b32_e32 v42, 16, v160
	v_and_b32_e32 v43, 0xffff0000, v160
	v_pk_add_f32 v[94:95], v[94:95], v[16:17]
	v_pk_mul_f32 v[72:73], v[72:73], v[108:109]
	v_pk_fma_f32 v[36:37], v[48:49], v[42:43], v[36:37]
	v_pk_mul_f32 v[72:73], v[94:95], v[72:73]
	v_pk_add_f32 v[36:37], v[36:37], v[56:57]
	v_pk_mul_f32 v[38:39], v[38:39], v[40:41]
	v_pk_add_f32 v[4:5], v[4:5], v[16:17]
	v_pk_mul_f32 v[6:7], v[6:7], v[10:11]
	v_cvt_pk_bf16_f32 v102, v102, v103
	v_cvt_pk_bf16_f32 v103, v104, v105
	v_cvt_pk_bf16_f32 v104, v106, v107
	v_cvt_pk_bf16_f32 v105, v72, v73
	v_mad_i64_i32 v[72:73], s[0:1], v163, s91, v[130:131]
	global_store_dwordx4 v[72:73], v[102:105], off sc1 nt
	s_nop 2
	v_pk_mul_f32 v[36:37], v[36:37], v[38:39]
	v_pk_mul_f32 v[8:9], v[4:5], v[6:7]
	v_cvt_pk_bf16_f32 v4, v34, v35
	v_cvt_pk_bf16_f32 v5, v36, v37
	v_cvt_pk_bf16_f32 v6, v2, v3
	v_cvt_pk_bf16_f32 v7, v8, v9
	v_mad_i64_i32 v[2:3], s[0:1], v155, s91, v[130:131]
	global_store_dwordx4 v[2:3], v[4:7], off sc1 nt
	s_nop 2
	s_andn2_b64 exec, exec, s[82:83]
	s_cbranch_execnz .LBB0_189
